# stagger waves 4-7 by half a tile in GQA+MLA attention loops (extra mid barrier, K LDS write moved before it); P0 weight-transpose items dealt round-robin across jobs
# speedup vs baseline: 1.0120x; 1.0120x over previous
.LBB0_105:
	s_lshr_b32 s0, s21, 3
	s_bfe_u32 s34, s0, 0x20002
	s_ashr_i32 s0, s21, 7
	s_lshl_b32 s1, s0, 12
	s_lshl_b32 s28, s21, 9
	s_bfe_u32 s35, s21, 0x40003
	s_addk_i32 s1, 0x2000
	s_and_b32 s38, s28, 0xe00
	s_lshl_b32 s0, s0, 9
	v_mov_b32_e32 v177, v197
	s_lshl_b32 s31, s34, 7
	s_or_b32 s28, s1, s38
	s_add_i32 s0, s1, s0
	s_lshl_b32 s29, s35, 6
	s_lshl_b32 s1, s21, 1
	v_and_b32_e32 v4, 0xffffffdf, v177
	s_lshl_b32 s35, s35, 7
	v_bfe_u32 v6, v177, 5, 1
	s_add_u32 s36, s48, s35
	v_add_u32_e32 v4, s28, v4
	s_addc_u32 s37, s49, 0
	v_lshlrev_b32_e32 v0, 4, v6
	v_ashrrev_i32_e32 v5, 31, v4
	v_lshl_add_u64 v[2:3], s[36:37], 0, v[0:1]
	v_lshlrev_b64 v[4:5], 11, v[4:5]
	v_lshl_add_u64 v[4:5], v[2:3], 0, v[4:5]
	global_load_dwordx4 v[18:21], v[4:5], off offset:32
	global_load_dwordx4 v[22:25], v[4:5], off offset:96
	global_load_dwordx4 v[26:29], v[4:5], off
	global_load_dwordx4 v[30:33], v[4:5], off offset:64
	v_add_u32_e32 v7, s38, v177
	v_lshlrev_b32_e32 v176, 3, v6
	v_ashrrev_i32_e32 v7, 6, v7
	v_cvt_f32_i32_e32 v54, v7
	v_cvt_f32_ubyte0_e32 v7, v176
	v_or_b32_e32 v4, 1, v176
	v_mul_f32_e32 v7, 0xbf549a78, v7
	v_exp_f32_e32 v70, v7
	v_cvt_f32_ubyte0_e32 v4, v4
	v_or_b32_e32 v5, 2, v176
	v_mul_f32_e32 v4, 0xbf549a78, v4
	v_exp_f32_e32 v71, v4
	v_cvt_f32_ubyte0_e32 v5, v5
	v_or_b32_e32 v10, 3, v176
	v_mul_f32_e32 v5, 0xbf549a78, v5
	v_lshlrev_b32_e32 v122, 5, v6
	v_mul_f32_e32 v6, v70, v54
	v_exp_f32_e32 v76, v5
	v_cvt_f32_ubyte0_e32 v5, v10
	v_or_b32_e32 v11, 4, v176
	v_mul_f32_e32 v4, 0.15915494, v6
	v_mul_f32_e32 v5, 0xbf549a78, v5
	v_cos_f32_e32 v6, v4
	v_sin_f32_e32 v8, v4
	v_mul_f32_e32 v4, v71, v54
	v_exp_f32_e32 v77, v5
	v_cvt_f32_ubyte0_e32 v5, v11
	v_or_b32_e32 v14, 5, v176
	v_mul_f32_e32 v4, 0.15915494, v4
	v_mul_f32_e32 v5, 0xbf549a78, v5
	v_cos_f32_e32 v7, v4
	v_sin_f32_e32 v9, v4
	v_mul_f32_e32 v4, v76, v54
	v_exp_f32_e32 v90, v5
	v_cvt_f32_ubyte0_e32 v5, v14
	v_or_b32_e32 v15, 6, v176
	v_mul_f32_e32 v4, 0.15915494, v4
	v_mul_f32_e32 v5, 0xbf549a78, v5
	v_cos_f32_e32 v10, v4
	v_sin_f32_e32 v12, v4
	v_mul_f32_e32 v4, v77, v54
	v_exp_f32_e32 v91, v5
	v_cvt_f32_ubyte0_e32 v5, v15
	v_mul_f32_e32 v4, 0.15915494, v4
	v_mul_f32_e32 v5, 0xbf549a78, v5
	v_cos_f32_e32 v11, v4
	v_sin_f32_e32 v13, v4
	v_mul_f32_e32 v4, v90, v54
	v_exp_f32_e32 v92, v5
	v_mul_f32_e32 v4, 0.15915494, v4
	v_cos_f32_e32 v14, v4
	v_sin_f32_e32 v16, v4
	v_mul_f32_e32 v4, v91, v54
	v_mul_f32_e32 v4, 0.15915494, v4
	v_or_b32_e32 v34, 7, v176
	v_cos_f32_e32 v15, v4
	v_sin_f32_e32 v17, v4
	v_mul_f32_e32 v4, v92, v54
	v_mul_f32_e32 v55, 0.15915494, v4
	v_cvt_f32_ubyte0_e32 v4, v34
	v_mul_f32_e32 v4, 0xbf549a78, v4
	v_exp_f32_e32 v93, v4
	v_and_b32_e32 v183, 31, v177
	v_cvt_f32_ubyte0_e32 v65, v183
	s_mov_b32 s36, 0x3c800000
	s_mov_b32 s38, 0x3e38aa3b
	s_and_b32 s35, s1, 0xc0
	s_lshl_b32 s80, s35, 1
	s_ashr_i32 s1, s0, 31
	v_mov_b32_e32 v182, 0xf149f2ca
	v_mov_b32_e32 v194, 0xf149f2ca
	v_mov_b32_e32 v203, 0
	s_waitcnt vmcnt(0)
	v_and_b32_e32 v79, 0xffff0000, v18
	v_lshlrev_b32_e32 v78, 16, v18
	s_waitcnt vmcnt(1)
	v_and_b32_e32 v111, 0xffff0000, v26
	v_lshlrev_b32_e32 v110, 16, v26
	v_and_b32_e32 v103, 0xffff0000, v27
	v_lshlrev_b32_e32 v102, 16, v27
	v_pk_mul_f32 v[26:27], v[110:111], v[110:111]
	v_pk_mul_f32 v[50:51], v[102:103], v[102:103]
	v_add_f32_e32 v26, v26, v27
	v_and_b32_e32 v95, 0xffff0000, v28
	v_lshlrev_b32_e32 v94, 16, v28
	v_add_f32_e32 v26, v50, v26
	v_and_b32_e32 v87, 0xffff0000, v29
	v_lshlrev_b32_e32 v86, 16, v29
	v_pk_mul_f32 v[28:29], v[94:95], v[94:95]
	v_add_f32_e32 v26, v51, v26
	v_add_f32_e32 v26, v28, v26
	v_pk_mul_f32 v[42:43], v[86:87], v[86:87]
	v_add_f32_e32 v26, v29, v26
	v_add_f32_e32 v26, v42, v26
	v_and_b32_e32 v73, 0xffff0000, v19
	v_lshlrev_b32_e32 v72, 16, v19
	v_pk_mul_f32 v[18:19], v[78:79], v[78:79]
	v_add_f32_e32 v26, v43, v26
	v_add_f32_e32 v18, v18, v26
	v_pk_mul_f32 v[36:37], v[72:73], v[72:73]
	v_add_f32_e32 v18, v19, v18
	v_and_b32_e32 v63, 0xffff0000, v20
	v_lshlrev_b32_e32 v62, 16, v20
	v_add_f32_e32 v18, v36, v18
	v_and_b32_e32 v49, 0xffff0000, v21
	v_lshlrev_b32_e32 v48, 16, v21
	v_pk_mul_f32 v[20:21], v[62:63], v[62:63]
	v_add_f32_e32 v18, v37, v18
	v_add_f32_e32 v18, v20, v18
	v_pk_mul_f32 v[4:5], v[48:49], v[48:49]
	v_add_f32_e32 v18, v21, v18
	s_waitcnt vmcnt(0)
	v_and_b32_e32 v105, 0xffff0000, v30
	v_lshlrev_b32_e32 v104, 16, v30
	v_add_f32_e32 v4, v4, v18
	v_and_b32_e32 v97, 0xffff0000, v31
	v_lshlrev_b32_e32 v96, 16, v31
	v_pk_mul_f32 v[30:31], v[104:105], v[104:105]
	v_add_f32_e32 v4, v5, v4
	v_add_f32_e32 v4, v30, v4
	v_pk_mul_f32 v[52:53], v[96:97], v[96:97]
	v_add_f32_e32 v4, v31, v4
	v_and_b32_e32 v89, 0xffff0000, v32
	v_lshlrev_b32_e32 v88, 16, v32
	v_add_f32_e32 v4, v52, v4
	v_and_b32_e32 v81, 0xffff0000, v33
	v_lshlrev_b32_e32 v80, 16, v33
	v_pk_mul_f32 v[32:33], v[88:89], v[88:89]
	v_add_f32_e32 v4, v53, v4
	v_add_f32_e32 v4, v32, v4
	v_pk_mul_f32 v[46:47], v[80:81], v[80:81]
	v_add_f32_e32 v4, v33, v4
	v_and_b32_e32 v75, 0xffff0000, v22
	v_lshlrev_b32_e32 v74, 16, v22
	v_add_f32_e32 v4, v46, v4
	v_and_b32_e32 v69, 0xffff0000, v23
	v_lshlrev_b32_e32 v68, 16, v23
	v_pk_mul_f32 v[22:23], v[74:75], v[74:75]
	v_add_f32_e32 v4, v47, v4
	v_add_f32_e32 v4, v22, v4
	v_pk_mul_f32 v[38:39], v[68:69], v[68:69]
	v_add_f32_e32 v4, v23, v4
	v_and_b32_e32 v45, 0xffff0000, v24
	v_lshlrev_b32_e32 v44, 16, v24
	v_add_f32_e32 v4, v38, v4
	v_and_b32_e32 v41, 0xffff0000, v25
	v_lshlrev_b32_e32 v40, 16, v25
	v_pk_mul_f32 v[24:25], v[44:45], v[44:45]
	v_add_f32_e32 v4, v39, v4
	v_add_f32_e32 v4, v24, v4
	v_pk_mul_f32 v[34:35], v[40:41], v[40:41]
	v_add_f32_e32 v4, v25, v4
	v_add_f32_e32 v4, v34, v4
	v_add_f32_e32 v119, v35, v4
	v_or_b32_e32 v4, 32, v177
	v_add_u32_e32 v4, s28, v4
	v_ashrrev_i32_e32 v5, 31, v4
	v_lshlrev_b64 v[4:5], 11, v[4:5]
	v_mov_b32_e32 v121, v119
	v_lshl_add_u64 v[2:3], v[2:3], 0, v[4:5]
	v_nop
	v_nop
	v_permlane32_swap_b32 v119, v121
	global_load_dwordx4 v[112:115], v[2:3], off
	global_load_dwordx4 v[82:85], v[2:3], off offset:32
	global_load_dwordx4 v[124:127], v[2:3], off offset:64
	global_load_dwordx4 v[98:101], v[2:3], off offset:96
	v_mul_f32_e32 v2, v93, v54
	v_mul_f32_e32 v2, 0.15915494, v2
	v_cos_f32_e32 v19, v2
	v_sin_f32_e32 v21, v2
	v_mul_f32_e32 v2, v70, v65
	v_mul_f32_e32 v2, 0.15915494, v2
	v_cos_f32_e32 v50, v2
	v_sin_f32_e32 v52, v2
	v_mul_f32_e32 v2, v71, v65
	v_mul_f32_e32 v2, 0.15915494, v2
	v_cos_f32_e32 v51, v2
	v_sin_f32_e32 v53, v2
	v_mul_f32_e32 v2, v76, v65
	v_mul_f32_e32 v2, 0.15915494, v2
	v_cos_f32_e32 v54, v2
	v_sin_f32_e32 v56, v2
	v_mul_f32_e32 v2, v77, v65
	v_mul_f32_e32 v2, 0.15915494, v2
	v_cos_f32_e32 v18, v55
	v_sin_f32_e32 v20, v55
	v_cos_f32_e32 v55, v2
	v_sin_f32_e32 v57, v2
	v_mul_f32_e32 v2, v90, v65
	v_mul_f32_e32 v2, 0.15915494, v2
	v_cos_f32_e32 v58, v2
	v_sin_f32_e32 v60, v2
	v_mul_f32_e32 v2, v91, v65
	v_mul_f32_e32 v2, 0.15915494, v2
	v_cos_f32_e32 v59, v2
	v_sin_f32_e32 v61, v2
	v_mul_f32_e32 v2, v92, v65
	v_mul_f32_e32 v2, 0.15915494, v2
	v_cos_f32_e32 v64, v2
	v_sin_f32_e32 v66, v2
	v_mul_f32_e32 v2, v93, v65
	v_mul_f32_e32 v2, 0.15915494, v2
	v_cos_f32_e32 v65, v2
	v_sin_f32_e32 v67, v2
	s_waitcnt lgkmcnt(0)
	global_load_dwordx4 v[128:131], v122, s[8:9] offset:16
	global_load_dwordx4 v[132:135], v122, s[8:9]
	global_load_dwordx4 v[136:139], v122, s[8:9] offset:80
	global_load_dwordx4 v[140:143], v122, s[8:9] offset:64
	global_load_dwordx4 v[144:147], v122, s[8:9] offset:144
	global_load_dwordx4 v[148:151], v122, s[8:9] offset:128
	global_load_dwordx4 v[2:5], v122, s[8:9] offset:208
	global_load_dwordx4 v[152:155], v122, s[8:9] offset:192
	v_bitop3_b32 v22, v177, 63, 32 bitop3:0xc8
	v_cvt_f32_ubyte0_e32 v35, v22
	v_mul_f32_e32 v22, v70, v35
	v_mul_f32_e32 v26, v76, v35
	v_mul_f32_e32 v30, v90, v35
	v_mul_f32_e32 v23, 0.15915494, v22
	v_mul_f32_e32 v27, 0.15915494, v26
	v_mul_f32_e32 v31, 0.15915494, v30
	v_cos_f32_e32 v22, v23
	v_sin_f32_e32 v24, v23
	v_mul_f32_e32 v23, v71, v35
	v_cos_f32_e32 v26, v27
	v_sin_f32_e32 v28, v27
	v_mul_f32_e32 v27, v77, v35
	v_cos_f32_e32 v30, v31
	v_sin_f32_e32 v32, v31
	v_mul_f32_e32 v31, v91, v35
	v_mul_f32_e32 v34, v92, v35
	v_mul_f32_e32 v35, v93, v35
	v_mul_f32_e32 v25, 0.15915494, v23
	v_cos_f32_e32 v23, v25
	v_sin_f32_e32 v25, v25
	v_mul_f32_e32 v29, 0.15915494, v27
	v_cos_f32_e32 v27, v29
	v_sin_f32_e32 v29, v29
	v_mul_f32_e32 v33, 0.15915494, v31
	v_cos_f32_e32 v31, v33
	v_sin_f32_e32 v33, v33
	v_mul_f32_e32 v36, 0.15915494, v34
	v_cos_f32_e32 v34, v36
	v_sin_f32_e32 v36, v36
	s_waitcnt vmcnt(11)
	v_and_b32_e32 v117, 0xffff0000, v112
	v_lshlrev_b32_e32 v116, 16, v112
	v_and_b32_e32 v109, 0xffff0000, v114
	s_waitcnt vmcnt(8)
	v_and_b32_e32 v39, 0xffff0000, v101
	v_lshlrev_b32_e32 v38, 16, v101
	v_and_b32_e32 v43, 0xffff0000, v100
	v_lshlrev_b32_e32 v42, 16, v100
	v_and_b32_e32 v101, 0xffff0000, v115
	v_lshlrev_b32_e32 v100, 16, v115
	v_lshlrev_b32_e32 v108, 16, v114
	v_and_b32_e32 v115, 0xffff0000, v113
	v_lshlrev_b32_e32 v114, 16, v113
	v_and_b32_e32 v107, 0xffff0000, v125
	v_lshlrev_b32_e32 v106, 16, v125
	v_and_b32_e32 v113, 0xffff0000, v124
	v_lshlrev_b32_e32 v112, 16, v124
	v_pk_mul_f32 v[124:125], v[116:117], v[116:117]
	v_pk_mul_f32 v[180:181], v[114:115], v[114:115]
	v_add_f32_e32 v37, v124, v125
	v_add_f32_e32 v37, v180, v37
	v_and_b32_e32 v71, 0xffff0000, v85
	v_lshlrev_b32_e32 v70, 16, v85
	v_and_b32_e32 v77, 0xffff0000, v84
	v_lshlrev_b32_e32 v76, 16, v84
	v_and_b32_e32 v85, 0xffff0000, v83
	v_lshlrev_b32_e32 v84, 16, v83
	v_and_b32_e32 v47, 0xffff0000, v99
	v_lshlrev_b32_e32 v46, 16, v99
	v_and_b32_e32 v91, 0xffff0000, v82
	v_lshlrev_b32_e32 v90, 16, v82
	v_and_b32_e32 v83, 0xffff0000, v98
	v_lshlrev_b32_e32 v82, 16, v98
	v_and_b32_e32 v93, 0xffff0000, v127
	v_lshlrev_b32_e32 v92, 16, v127
	v_and_b32_e32 v99, 0xffff0000, v126
	v_lshlrev_b32_e32 v98, 16, v126
	v_pk_mul_f32 v[126:127], v[108:109], v[108:109]
	v_add_f32_e32 v37, v181, v37
	v_add_f32_e32 v37, v126, v37
	v_pk_mul_f32 v[172:173], v[100:101], v[100:101]
	v_add_f32_e32 v37, v127, v37
	v_add_f32_e32 v37, v172, v37
	v_pk_mul_f32 v[168:169], v[90:91], v[90:91]
	v_add_f32_e32 v37, v173, v37
	v_add_f32_e32 v37, v168, v37
	v_pk_mul_f32 v[164:165], v[84:85], v[84:85]
	v_add_f32_e32 v37, v169, v37
	v_add_f32_e32 v37, v164, v37
	v_pk_mul_f32 v[160:161], v[76:77], v[76:77]
	v_add_f32_e32 v37, v165, v37
	v_add_f32_e32 v37, v160, v37
	v_pk_mul_f32 v[156:157], v[70:71], v[70:71]
	v_add_f32_e32 v37, v161, v37
	v_add_f32_e32 v37, v156, v37
	v_pk_mul_f32 v[186:187], v[112:113], v[112:113]
	v_add_f32_e32 v37, v157, v37
	v_add_f32_e32 v37, v186, v37
	v_pk_mul_f32 v[184:185], v[106:107], v[106:107]
	v_add_f32_e32 v37, v187, v37
	v_add_f32_e32 v37, v184, v37
	v_pk_mul_f32 v[178:179], v[98:99], v[98:99]
	v_add_f32_e32 v37, v185, v37
	v_add_f32_e32 v37, v178, v37
	v_pk_mul_f32 v[174:175], v[92:93], v[92:93]
	v_add_f32_e32 v37, v179, v37
	v_add_f32_e32 v37, v174, v37
	v_pk_mul_f32 v[170:171], v[82:83], v[82:83]
	v_add_f32_e32 v37, v175, v37
	v_add_f32_e32 v37, v170, v37
	v_pk_mul_f32 v[166:167], v[46:47], v[46:47]
	v_add_f32_e32 v37, v171, v37
	v_add_f32_e32 v37, v166, v37
	v_pk_mul_f32 v[162:163], v[42:43], v[42:43]
	v_add_f32_e32 v37, v167, v37
	v_add_f32_e32 v37, v162, v37
	v_pk_mul_f32 v[158:159], v[38:39], v[38:39]
	v_add_f32_e32 v37, v163, v37
	v_add_f32_e32 v37, v158, v37
	v_add_f32_e32 v118, v159, v37
	v_mov_b32_e32 v120, v118
	v_nop
	v_nop
	v_permlane32_swap_b32 v118, v120
	v_mov_b32_e32 v185, 0
	v_pk_add_f32 v[118:119], v[118:119], v[120:121]
	s_nop 0
	v_pk_fma_f32 v[126:127], v[118:119], s[36:37], v[252:253] op_sel_hi:[1,0,0]
	s_nop 0
	v_mul_f32_e32 v37, 0x4b800000, v127
	v_cmp_gt_f32_e32 vcc, s67, v127
	s_nop 1
	v_cndmask_b32_e32 v37, v127, v37, vcc
	v_rsq_f32_e32 v118, v37
	v_mul_f32_e32 v37, 0.15915494, v35
	v_cos_f32_e32 v35, v37
	v_sin_f32_e32 v37, v37
	v_mul_f32_e32 v119, 0x45800000, v118
	v_cndmask_b32_e32 v118, v118, v119, vcc
	s_waitcnt vmcnt(6)
	v_pk_mul_f32 v[120:121], v[132:133], v[118:119] op_sel_hi:[1,0]
	s_waitcnt vmcnt(1)
	v_pk_mul_f32 v[2:3], v[118:119], v[2:3] op_sel_hi:[0,1]
	v_pk_mul_f32 v[110:111], v[120:121], v[110:111]
	v_pk_mul_f32 v[120:121], v[134:135], v[118:119] op_sel_hi:[1,0]
	v_pk_mul_f32 v[44:45], v[2:3], v[44:45]
	v_pk_mul_f32 v[132:133], v[120:121], v[102:103]
	v_pk_mul_f32 v[102:103], v[128:129], v[118:119] op_sel_hi:[1,0]
	v_pk_mul_f32 v[2:3], v[118:119], v[4:5] op_sel_hi:[0,1]
	v_pk_mul_f32 v[128:129], v[102:103], v[94:95]
	v_pk_mul_f32 v[94:95], v[130:131], v[118:119] op_sel_hi:[1,0]
	v_pk_mul_f32 v[40:41], v[2:3], v[40:41]
	v_pk_mul_f32 v[130:131], v[94:95], v[86:87]
	v_pk_mul_f32 v[86:87], v[118:119], v[140:141] op_sel_hi:[0,1]
	v_pk_mul_f32 v[134:135], v[86:87], v[78:79]
	v_pk_mul_f32 v[78:79], v[118:119], v[142:143] op_sel_hi:[0,1]
	v_pk_mul_f32 v[140:141], v[78:79], v[72:73]
	v_pk_mul_f32 v[72:73], v[118:119], v[136:137] op_sel_hi:[0,1]
	v_pk_mul_f32 v[62:63], v[72:73], v[62:63]
	v_pk_mul_f32 v[72:73], v[118:119], v[138:139] op_sel_hi:[0,1]
	v_pk_mul_f32 v[48:49], v[72:73], v[48:49]
	v_pk_mul_f32 v[72:73], v[118:119], v[148:149] op_sel_hi:[0,1]
	v_pk_mul_f32 v[136:137], v[72:73], v[104:105]
	v_pk_mul_f32 v[72:73], v[118:119], v[150:151] op_sel_hi:[0,1]
	v_pk_mul_f32 v[138:139], v[72:73], v[96:97]
	v_pk_mul_f32 v[72:73], v[118:119], v[144:145] op_sel_hi:[0,1]
	v_pk_mul_f32 v[142:143], v[72:73], v[88:89]
	v_pk_mul_f32 v[72:73], v[118:119], v[146:147] op_sel_hi:[0,1]
	v_pk_mul_f32 v[144:145], v[72:73], v[80:81]
	s_waitcnt vmcnt(0)
	v_pk_mul_f32 v[72:73], v[118:119], v[152:153] op_sel_hi:[0,1]
	v_pk_mul_f32 v[94:95], v[10:11], v[138:139]
	v_pk_mul_f32 v[146:147], v[72:73], v[74:75]
	v_pk_mul_f32 v[72:73], v[118:119], v[154:155] op_sel_hi:[0,1]
	v_pk_mul_f32 v[2:3], v[6:7], v[136:137]
	v_pk_fma_f32 v[154:155], v[12:13], v[132:133], v[94:95]
	v_pk_mul_f32 v[94:95], v[14:15], v[142:143]
	v_pk_mul_f32 v[68:69], v[72:73], v[68:69]
	global_load_dwordx4 v[72:75], v122, s[8:9] offset:16
	global_load_dwordx4 v[78:81], v122, s[8:9]
	v_pk_fma_f32 v[152:153], v[8:9], v[110:111], v[2:3]
	global_load_dwordx4 v[2:5], v122, s[8:9] offset:80
	global_load_dwordx4 v[86:89], v122, s[8:9] offset:64
	v_pk_fma_f32 v[160:161], v[16:17], v[128:129], v[94:95]
	v_pk_mul_f32 v[94:95], v[18:19], v[144:145]
	v_pk_mul_f32 v[118:119], v[50:51], v[146:147]
	v_pk_fma_f32 v[162:163], v[20:21], v[130:131], v[94:95]
	global_load_dwordx4 v[94:97], v122, s[8:9] offset:144
	global_load_dwordx4 v[102:105], v122, s[8:9] offset:128
	v_pk_fma_f32 v[164:165], v[52:53], v[134:135], v[118:119]
	v_pk_mul_f32 v[118:119], v[54:55], v[68:69]
	v_pk_mul_f32 v[136:137], v[8:9], v[136:137]
	v_pk_fma_f32 v[166:167], v[56:57], v[140:141], v[118:119]
	v_pk_mul_f32 v[118:119], v[58:59], v[44:45]
	v_pk_mul_f32 v[148:149], v[64:65], v[40:41]
	v_pk_fma_f32 v[168:169], v[60:61], v[62:63], v[118:119]
	global_load_dwordx4 v[118:121], v122, s[8:9] offset:208
	s_nop 0
	global_load_dwordx4 v[122:125], v122, s[8:9] offset:192
	v_pk_fma_f32 v[110:111], v[6:7], v[110:111], v[136:137] neg_lo:[0,0,1] neg_hi:[0,0,1]
	v_pk_mul_f32 v[40:41], v[66:67], v[40:41]
	v_pk_mul_f32 v[110:111], v[110:111], s[38:39] op_sel_hi:[1,0]
	v_pk_fma_f32 v[40:41], v[64:65], v[48:49], v[40:41] neg_lo:[0,0,1] neg_hi:[0,0,1]
	v_cvt_pk_bf16_f32 v156, v110, v111
	v_pk_mul_f32 v[110:111], v[12:13], v[138:139]
	v_pk_mul_f32 v[44:45], v[60:61], v[44:45]
	v_pk_mul_f32 v[40:41], v[40:41], s[38:39] op_sel_hi:[1,0]
	v_pk_fma_f32 v[110:111], v[10:11], v[132:133], v[110:111] neg_lo:[0,0,1] neg_hi:[0,0,1]
	v_pk_fma_f32 v[44:45], v[58:59], v[62:63], v[44:45] neg_lo:[0,0,1] neg_hi:[0,0,1]
	v_cvt_pk_bf16_f32 v151, v40, v41
	v_pk_mul_f32 v[40:41], v[152:153], s[38:39] op_sel_hi:[1,0]
	v_pk_mul_f32 v[110:111], v[110:111], s[38:39] op_sel_hi:[1,0]
	v_pk_mul_f32 v[44:45], v[44:45], s[38:39] op_sel_hi:[1,0]
	v_cvt_pk_bf16_f32 v152, v40, v41
	v_pk_mul_f32 v[40:41], v[154:155], s[38:39] op_sel_hi:[1,0]
	v_cvt_pk_bf16_f32 v157, v110, v111
	v_pk_mul_f32 v[110:111], v[16:17], v[142:143]
	v_cvt_pk_bf16_f32 v150, v44, v45
	v_cvt_pk_bf16_f32 v153, v40, v41
	v_pk_mul_f32 v[40:41], v[160:161], s[38:39] op_sel_hi:[1,0]
	v_mul_f32_e32 v44, 0x4b800000, v126
	v_cmp_gt_f32_e32 vcc, s67, v126
	v_pk_fma_f32 v[110:111], v[14:15], v[128:129], v[110:111] neg_lo:[0,0,1] neg_hi:[0,0,1]
	v_cvt_pk_bf16_f32 v154, v40, v41
	v_pk_mul_f32 v[40:41], v[162:163], s[38:39] op_sel_hi:[1,0]
	v_cndmask_b32_e32 v44, v126, v44, vcc
	v_pk_mul_f32 v[110:111], v[110:111], s[38:39] op_sel_hi:[1,0]
	v_cvt_pk_bf16_f32 v155, v40, v41
	v_pk_mul_f32 v[40:41], v[164:165], s[38:39] op_sel_hi:[1,0]
	v_rsq_f32_e32 v44, v44
	v_cvt_pk_bf16_f32 v158, v110, v111
	v_pk_mul_f32 v[110:111], v[20:21], v[144:145]
	v_cvt_pk_bf16_f32 v144, v40, v41
	v_pk_mul_f32 v[40:41], v[166:167], s[38:39] op_sel_hi:[1,0]
	v_pk_fma_f32 v[170:171], v[66:67], v[48:49], v[148:149]
	v_cvt_pk_bf16_f32 v145, v40, v41
	v_pk_mul_f32 v[40:41], v[168:169], s[38:39] op_sel_hi:[1,0]
	v_pk_mul_f32 v[52:53], v[52:53], v[146:147]
	v_cvt_pk_bf16_f32 v146, v40, v41
	v_pk_mul_f32 v[40:41], v[170:171], s[38:39] op_sel_hi:[1,0]
	v_pk_fma_f32 v[50:51], v[50:51], v[134:135], v[52:53] neg_lo:[0,0,1] neg_hi:[0,0,1]
	v_cvt_pk_bf16_f32 v147, v40, v41
	v_mul_f32_e32 v40, 0x45800000, v44
	v_cndmask_b32_e32 v40, v44, v40, vcc
	v_pk_mul_f32 v[50:51], v[50:51], s[38:39] op_sel_hi:[1,0]
	v_pk_fma_f32 v[110:111], v[18:19], v[130:131], v[110:111] neg_lo:[0,0,1] neg_hi:[0,0,1]
	v_cvt_pk_bf16_f32 v148, v50, v51
	v_pk_mul_f32 v[50:51], v[56:57], v[68:69]
	v_pk_mul_f32 v[110:111], v[110:111], s[38:39] op_sel_hi:[1,0]
	v_pk_fma_f32 v[50:51], v[54:55], v[140:141], v[50:51] neg_lo:[0,0,1] neg_hi:[0,0,1]
	v_cvt_pk_bf16_f32 v159, v110, v111
	v_pk_mul_f32 v[50:51], v[50:51], s[38:39] op_sel_hi:[1,0]
	s_waitcnt vmcnt(6)
	v_pk_mul_f32 v[48:49], v[80:81], v[40:41] op_sel_hi:[1,0]
	s_waitcnt vmcnt(5)
	v_pk_mul_f32 v[2:3], v[40:41], v[2:3] op_sel_hi:[0,1]
	v_pk_mul_f32 v[62:63], v[2:3], v[76:77]
	v_pk_mul_f32 v[2:3], v[40:41], v[4:5] op_sel_hi:[0,1]
	v_pk_mul_f32 v[64:65], v[2:3], v[70:71]
	v_pk_mul_f32 v[52:53], v[48:49], v[114:115]
	v_pk_mul_f32 v[48:49], v[72:73], v[40:41] op_sel_hi:[1,0]
	s_waitcnt vmcnt(2)
	v_pk_mul_f32 v[2:3], v[40:41], v[102:103] op_sel_hi:[0,1]
	v_pk_mul_f32 v[66:67], v[2:3], v[112:113]
	v_pk_mul_f32 v[2:3], v[40:41], v[104:105] op_sel_hi:[0,1]
	v_pk_mul_f32 v[68:69], v[2:3], v[106:107]
	v_pk_mul_f32 v[2:3], v[40:41], v[94:95] op_sel_hi:[0,1]
	v_pk_mul_f32 v[70:71], v[2:3], v[98:99]
	v_pk_mul_f32 v[2:3], v[40:41], v[96:97] op_sel_hi:[0,1]
	v_pk_mul_f32 v[72:73], v[2:3], v[92:93]
	s_waitcnt vmcnt(0)
	v_pk_mul_f32 v[2:3], v[40:41], v[122:123] op_sel_hi:[0,1]
	v_ashrrev_i32_e32 v94, 3, v177
	v_pk_mul_f32 v[54:55], v[48:49], v[108:109]
	v_pk_mul_f32 v[48:49], v[74:75], v[40:41] op_sel_hi:[1,0]
	v_pk_mul_f32 v[74:75], v[2:3], v[82:83]
	v_add_u32_e32 v2, s0, v94
	v_ashrrev_i32_e32 v3, 31, v2
	v_pk_mul_f32 v[44:45], v[78:79], v[40:41] op_sel_hi:[1,0]
	v_lshlrev_b64 v[78:79], 9, v[2:3]
	v_lshlrev_b32_e32 v95, 4, v177
	v_lshl_add_u64 v[2:3], s[10:11], 0, v[78:79]
	v_pk_mul_f32 v[56:57], v[48:49], v[100:101]
	v_pk_mul_f32 v[48:49], v[40:41], v[86:87] op_sel_hi:[0,1]
	v_and_b32_e32 v76, 0x70, v95
	v_mov_b32_e32 v77, v1
	v_lshl_add_u64 v[2:3], v[2:3], 0, s[80:81]
	v_pk_mul_f32 v[58:59], v[48:49], v[90:91]
	v_pk_mul_f32 v[48:49], v[40:41], v[88:89] op_sel_hi:[0,1]
	v_add_u32_e32 v41, s35, v94
	v_mov_b64_e32 v[4:5], s[18:19]
	v_lshl_add_u64 v[2:3], v[2:3], 0, v[76:77]
	v_pk_mul_f32 v[60:61], v[48:49], v[84:85]
	v_mad_i64_i32 v[48:49], s[36:37], v41, s68, v[4:5]
	global_load_dwordx4 v[2:5], v[2:3], off
	s_lshl_b64 s[0:1], s[0:1], 1
	v_lshl_add_u64 v[48:49], v[48:49], 0, s[0:1]
	v_lshl_add_u64 v[48:49], v[48:49], 0, v[76:77]
	v_cvt_pk_bf16_f32 v149, v50, v51
	global_load_dwordx4 v[48:51], v[48:49], off
	v_pk_mul_f32 v[80:81], v[40:41], v[124:125] op_sel_hi:[0,1]
	v_pk_mul_f32 v[46:47], v[80:81], v[46:47]
	v_pk_mul_f32 v[80:81], v[40:41], v[118:119] op_sel_hi:[0,1]
	v_pk_mul_f32 v[40:41], v[40:41], v[120:121] op_sel_hi:[0,1]
	v_pk_mul_f32 v[44:45], v[44:45], v[116:117]
	v_pk_mul_f32 v[38:39], v[40:41], v[38:39]
	v_pk_mul_f32 v[40:41], v[6:7], v[66:67]
	v_pk_mul_f32 v[42:43], v[80:81], v[42:43]
	v_pk_fma_f32 v[40:41], v[8:9], v[44:45], v[40:41]
	v_pk_mul_f32 v[8:9], v[8:9], v[66:67]
	v_pk_mul_f32 v[80:81], v[10:11], v[68:69]
	v_pk_fma_f32 v[6:7], v[6:7], v[44:45], v[8:9] neg_lo:[0,0,1] neg_hi:[0,0,1]
	v_pk_fma_f32 v[80:81], v[12:13], v[52:53], v[80:81]
	v_pk_mul_f32 v[6:7], v[6:7], s[38:39] op_sel_hi:[1,0]
	v_pk_mul_f32 v[82:83], v[14:15], v[70:71]
	v_cvt_pk_bf16_f32 v172, v6, v7
	v_pk_mul_f32 v[6:7], v[12:13], v[68:69]
	v_pk_fma_f32 v[82:83], v[16:17], v[54:55], v[82:83]
	v_pk_fma_f32 v[6:7], v[10:11], v[52:53], v[6:7] neg_lo:[0,0,1] neg_hi:[0,0,1]
	v_pk_mul_f32 v[84:85], v[18:19], v[72:73]
	v_pk_mul_f32 v[6:7], v[6:7], s[38:39] op_sel_hi:[1,0]
	v_pk_fma_f32 v[84:85], v[20:21], v[56:57], v[84:85]
	v_cvt_pk_bf16_f32 v173, v6, v7
	v_pk_mul_f32 v[6:7], v[16:17], v[70:71]
	v_pk_mul_f32 v[86:87], v[22:23], v[74:75]
	v_pk_fma_f32 v[6:7], v[14:15], v[54:55], v[6:7] neg_lo:[0,0,1] neg_hi:[0,0,1]
	v_pk_fma_f32 v[86:87], v[24:25], v[58:59], v[86:87]
	v_pk_mul_f32 v[6:7], v[6:7], s[38:39] op_sel_hi:[1,0]
	v_pk_mul_f32 v[88:89], v[26:27], v[46:47]
	v_cvt_pk_bf16_f32 v174, v6, v7
	v_pk_mul_f32 v[6:7], v[20:21], v[72:73]
	v_pk_fma_f32 v[88:89], v[28:29], v[60:61], v[88:89]
	v_pk_fma_f32 v[6:7], v[18:19], v[56:57], v[6:7] neg_lo:[0,0,1] neg_hi:[0,0,1]
	v_pk_mul_f32 v[90:91], v[30:31], v[42:43]
	v_pk_mul_f32 v[6:7], v[6:7], s[38:39] op_sel_hi:[1,0]
	v_pk_fma_f32 v[90:91], v[32:33], v[62:63], v[90:91]
	v_cvt_pk_bf16_f32 v175, v6, v7
	v_pk_mul_f32 v[6:7], v[24:25], v[74:75]
	v_pk_mul_f32 v[92:93], v[34:35], v[38:39]
	v_pk_fma_f32 v[6:7], v[22:23], v[58:59], v[6:7] neg_lo:[0,0,1] neg_hi:[0,0,1]
	v_pk_fma_f32 v[92:93], v[36:37], v[64:65], v[92:93]
	v_pk_mul_f32 v[6:7], v[6:7], s[38:39] op_sel_hi:[1,0]
	v_mul_lo_u32 v8, v94, s42
	v_cvt_pk_bf16_f32 v168, v6, v7
	v_pk_mul_f32 v[6:7], v[28:29], v[46:47]
	v_add3_u32 v192, 0, v8, v76
	v_pk_fma_f32 v[6:7], v[26:27], v[60:61], v[6:7] neg_lo:[0,0,1] neg_hi:[0,0,1]
	s_add_u32 s0, s17, s0
	v_pk_mul_f32 v[6:7], v[6:7], s[38:39] op_sel_hi:[1,0]
	s_addc_u32 s1, s20, s1
	v_cvt_pk_bf16_f32 v169, v6, v7
	v_pk_mul_f32 v[6:7], v[32:33], v[42:43]
	v_or3_b32 v78, v78, s31, v76
	v_pk_fma_f32 v[6:7], v[30:31], v[62:63], v[6:7] neg_lo:[0,0,1] neg_hi:[0,0,1]
	v_mov_b32_e32 v14, v1
	v_pk_mul_f32 v[6:7], v[6:7], s[38:39] op_sel_hi:[1,0]
	v_mov_b32_e32 v15, v1
	v_cvt_pk_bf16_f32 v170, v6, v7
	v_pk_mul_f32 v[6:7], v[36:37], v[38:39]
	v_lshl_add_u64 v[180:181], s[2:3], 0, v[78:79]
	v_pk_fma_f32 v[6:7], v[34:35], v[64:65], v[6:7] neg_lo:[0,0,1] neg_hi:[0,0,1]
	v_mov_b32_e32 v9, v1
	v_pk_mul_f32 v[6:7], v[6:7], s[38:39] op_sel_hi:[1,0]
	v_mov_b32_e32 v10, v1
	v_cvt_pk_bf16_f32 v171, v6, v7
	v_pk_mul_f32 v[6:7], v[40:41], s[38:39] op_sel_hi:[1,0]
	v_mov_b32_e32 v11, v1
	v_cvt_pk_bf16_f32 v164, v6, v7
	v_pk_mul_f32 v[6:7], v[80:81], s[38:39] op_sel_hi:[1,0]
	v_mov_b32_e32 v12, v1
	v_cvt_pk_bf16_f32 v165, v6, v7
	v_pk_mul_f32 v[6:7], v[82:83], s[38:39] op_sel_hi:[1,0]
	v_mov_b32_e32 v13, v1
	v_cvt_pk_bf16_f32 v166, v6, v7
	v_pk_mul_f32 v[6:7], v[84:85], s[38:39] op_sel_hi:[1,0]
	s_waitcnt vmcnt(1)
	ds_write_b128 v192, v[2:5]
	v_cvt_pk_bf16_f32 v167, v6, v7
	v_pk_mul_f32 v[6:7], v[86:87], s[38:39] op_sel_hi:[1,0]
	v_mov_b32_e32 v4, v1
	v_cvt_pk_bf16_f32 v160, v6, v7
	v_pk_mul_f32 v[6:7], v[88:89], s[38:39] op_sel_hi:[1,0]
	v_mov_b32_e32 v5, v1
	v_cvt_pk_bf16_f32 v161, v6, v7
	v_pk_mul_f32 v[6:7], v[90:91], s[38:39] op_sel_hi:[1,0]
	s_nop 0
	v_cvt_pk_bf16_f32 v162, v6, v7
	v_pk_mul_f32 v[6:7], v[92:93], s[38:39] op_sel_hi:[1,0]
	s_nop 0
	v_cvt_pk_bf16_f32 v163, v6, v7
	v_and_b32_e32 v6, 0x60, v95
	v_lshlrev_b32_e32 v7, 3, v177
	v_and_b32_e32 v7, 8, v7
	v_add_u32_e32 v2, 0, v6
	v_add3_u32 v193, v2, v7, v8
	v_add_u32_e32 v2, 0x4800, v193
	s_waitcnt vmcnt(0)
	ds_write2_b64 v2, v[48:49], v[50:51] offset1:2
	v_mul_u32_u24_e32 v2, 0x90, v183
	v_add3_u32 v190, 0, v2, v0
	v_mad_i64_i32 v[2:3], s[36:37], v94, s68, 0
	v_mov_b32_e32 v0, 0x220000
	v_mad_u64_u32 v[2:3], s[34:35], s34, v0, v[2:3]
	v_or_b32_e32 v2, v2, v76
	v_lshl_add_u64 v[178:179], s[0:1], 0, v[2:3]
	v_mov_b32_e32 v0, v1
	v_mov_b32_e32 v2, v1
	v_mov_b32_e32 v3, v1
	v_mov_b32_e32 v6, v1
	v_mov_b32_e32 v7, v1
	v_mov_b32_e32 v8, v1
	v_mov_b64_e32 v[30:31], v[14:15]
	v_mov_b64_e32 v[46:47], v[14:15]
	v_mov_b64_e32 v[62:63], v[14:15]
	v_mov_b64_e32 v[78:79], v[14:15]
	s_mov_b32 s0, 0
	v_mov_b64_e32 v[28:29], v[12:13]
	v_mov_b64_e32 v[26:27], v[10:11]
	v_mov_b64_e32 v[24:25], v[8:9]
	v_mov_b64_e32 v[22:23], v[6:7]
	v_mov_b64_e32 v[20:21], v[4:5]
	v_mov_b64_e32 v[18:19], v[2:3]
	v_mov_b64_e32 v[16:17], v[0:1]
	v_mov_b64_e32 v[44:45], v[12:13]
	v_mov_b64_e32 v[42:43], v[10:11]
	v_mov_b64_e32 v[40:41], v[8:9]
	v_mov_b64_e32 v[38:39], v[6:7]
	v_mov_b64_e32 v[36:37], v[4:5]
	v_mov_b64_e32 v[34:35], v[2:3]
	v_mov_b64_e32 v[32:33], v[0:1]
	v_mov_b64_e32 v[60:61], v[12:13]
	v_mov_b64_e32 v[58:59], v[10:11]
	v_mov_b64_e32 v[56:57], v[8:9]
	v_mov_b64_e32 v[54:55], v[6:7]
	v_mov_b64_e32 v[52:53], v[4:5]
	v_mov_b64_e32 v[50:51], v[2:3]
	v_mov_b64_e32 v[48:49], v[0:1]
	v_mov_b64_e32 v[76:77], v[12:13]
	v_mov_b64_e32 v[74:75], v[10:11]
	v_mov_b64_e32 v[72:73], v[8:9]
	v_mov_b64_e32 v[70:71], v[6:7]
	v_mov_b64_e32 v[68:69], v[4:5]
	v_mov_b64_e32 v[66:67], v[2:3]
	v_mov_b64_e32 v[64:65], v[0:1]
	s_mov_b64 s[34:35], 0x8000
	global_load_dwordx4 v[6:9], v[180:181], off
	v_lshl_add_u64 v[180:181], v[180:181], 0, s[34:35]
	v_readfirstlane_b32 s101, v197
	s_waitcnt lgkmcnt(0)
	s_barrier
	s_cmpk_lt_u32 s101, 0x100
	s_cbranch_scc1 .Lgqa_stag_in
	s_barrier
.Lgqa_stag_in:
.LBB0_106:
	global_load_dwordx4 v[2:5], v[178:179], off
	s_and_b32 s1, s0, 1
	s_mul_i32 s31, s1, 0x2400
	v_add_u32_e32 v202, s31, v190
	ds_read_b128 v[10:13], v202 offset:4608
	ds_read_b128 v[80:83], v202
	ds_read_b128 v[186:189], v202 offset:32
	v_mov_b32_e32 v0, v194
	s_waitcnt lgkmcnt(2)
	v_mfma_f32_32x32x16_bf16 v[112:127], v[10:13], v[156:159], 0
	s_waitcnt lgkmcnt(1)
	v_mfma_f32_32x32x16_bf16 v[128:143], v[80:83], v[156:159], 0
	v_mfma_f32_32x32x16_bf16 v[96:111], v[80:83], v[172:175], 0
	v_mfma_f32_32x32x16_bf16 v[80:95], v[10:13], v[172:175], 0
	ds_read_b128 v[10:13], v202 offset:4640
	s_waitcnt lgkmcnt(1)
	v_mfma_f32_32x32x16_bf16 v[128:143], v[186:189], v[148:151], v[128:143]
	s_waitcnt lgkmcnt(0)
	v_mfma_f32_32x32x16_bf16 v[112:127], v[10:13], v[148:151], v[112:127]
	v_mfma_f32_32x32x16_bf16 v[96:111], v[186:189], v[168:171], v[96:111]
	v_mfma_f32_32x32x16_bf16 v[80:95], v[10:13], v[168:171], v[80:95]
	ds_read_b128 v[10:13], v202 offset:64
	ds_read_b128 v[186:189], v202 offset:4672
	s_waitcnt lgkmcnt(1)
	v_mfma_f32_32x32x16_bf16 v[128:143], v[10:13], v[152:155], v[128:143]
	s_waitcnt lgkmcnt(0)
	v_mfma_f32_32x32x16_bf16 v[112:127], v[186:189], v[152:155], v[112:127]
	v_mfma_f32_32x32x16_bf16 v[96:111], v[10:13], v[164:167], v[96:111]
	v_mfma_f32_32x32x16_bf16 v[80:95], v[186:189], v[164:167], v[80:95]
	ds_read_b128 v[10:13], v202 offset:96
	ds_read_b128 v[186:189], v202 offset:4704
	s_waitcnt lgkmcnt(1)
	v_mfma_f32_32x32x16_bf16 v[128:143], v[10:13], v[144:147], v[128:143]
	s_waitcnt lgkmcnt(0)
	v_mfma_f32_32x32x16_bf16 v[112:127], v[186:189], v[144:147], v[112:127]
	v_mfma_f32_32x32x16_bf16 v[96:111], v[10:13], v[160:163], v[96:111]
	v_max3_f32 v10, v128, v112, v129
	s_nop 10
	v_max_f32_e32 v11, v127, v127
	v_max3_f32 v10, v10, v113, v130
	s_nop 0
	v_max3_f32 v10, v10, v114, v131
	s_nop 0
	v_max3_f32 v10, v10, v115, v132
	v_mfma_f32_32x32x16_bf16 v[80:95], v[186:189], v[160:163], v[80:95]
	v_max3_f32 v10, v10, v116, v133
	s_nop 0
	v_max3_f32 v10, v10, v117, v134
	s_nop 0
	v_max3_f32 v10, v10, v118, v135
	s_nop 0
	v_max3_f32 v10, v10, v119, v136
	s_nop 0
	v_max3_f32 v10, v10, v120, v137
	s_nop 0
	v_max3_f32 v10, v10, v121, v138
	s_nop 0
	v_max3_f32 v10, v10, v122, v139
	s_nop 0
	v_max3_f32 v10, v10, v123, v140
	s_nop 0
	v_max3_f32 v10, v10, v124, v141
	s_nop 0
	v_max3_f32 v10, v10, v125, v142
	s_nop 0
	v_max3_f32 v10, v10, v126, v143
	s_nop 0
	v_max_f32_e32 v10, v10, v10
	v_max_f32_e32 v10, v10, v11
	v_mov_b32_e32 v11, v10
	v_nop
	v_nop
	v_permlane32_swap_b32 v10, v11
	s_nop 0
	v_max3_f32 v194, v0, v10, v11
	v_sub_f32_e32 v0, v0, v194
	v_exp_f32_e32 v14, v0
	s_nop 0
	v_cmp_neq_f32_e32 vcc, 1.0, v14
	s_cbranch_vccz .LBB0_108
	v_pk_mul_f32 v[78:79], v[78:79], v[14:15] op_sel_hi:[1,0]
	v_pk_mul_f32 v[76:77], v[76:77], v[14:15] op_sel_hi:[1,0]
	v_pk_mul_f32 v[74:75], v[74:75], v[14:15] op_sel_hi:[1,0]
	v_pk_mul_f32 v[72:73], v[72:73], v[14:15] op_sel_hi:[1,0]
	v_pk_mul_f32 v[70:71], v[70:71], v[14:15] op_sel_hi:[1,0]
	v_pk_mul_f32 v[68:69], v[68:69], v[14:15] op_sel_hi:[1,0]
	v_pk_mul_f32 v[66:67], v[66:67], v[14:15] op_sel_hi:[1,0]
	v_pk_mul_f32 v[64:65], v[64:65], v[14:15] op_sel_hi:[1,0]
	v_pk_mul_f32 v[62:63], v[62:63], v[14:15] op_sel_hi:[1,0]
	v_pk_mul_f32 v[60:61], v[60:61], v[14:15] op_sel_hi:[1,0]
	v_pk_mul_f32 v[58:59], v[58:59], v[14:15] op_sel_hi:[1,0]
	v_pk_mul_f32 v[56:57], v[56:57], v[14:15] op_sel_hi:[1,0]
	v_pk_mul_f32 v[54:55], v[54:55], v[14:15] op_sel_hi:[1,0]
	v_pk_mul_f32 v[52:53], v[52:53], v[14:15] op_sel_hi:[1,0]
	v_pk_mul_f32 v[50:51], v[50:51], v[14:15] op_sel_hi:[1,0]
	v_pk_mul_f32 v[48:49], v[48:49], v[14:15] op_sel_hi:[1,0]

.LBB0_110:
	s_xor_b32 vcc_lo, s1, 1
	s_mulk_i32 vcc_lo, 0x2400
	v_add_u32_e32 v10, vcc_lo, v192
	s_waitcnt vmcnt(1)
	ds_write_b128 v10, v[6:9]
	s_mov_b64 s[34:35], 0x8000
	s_waitcnt lgkmcnt(0)
	s_barrier
	global_load_dwordx4 v[6:9], v[180:181], off
	v_lshl_add_u64 v[180:181], v[180:181], 0, s[34:35]
	v_sub_f32_e32 v96, v96, v195
	v_sub_f32_e32 v80, v80, v195
	v_exp_f32_e32 v96, v96
	v_exp_f32_e32 v215, v80
	v_sub_f32_e32 v97, v97, v195
	v_sub_f32_e32 v81, v81, v195
	v_exp_f32_e32 v97, v97
	v_exp_f32_e32 v216, v81
	v_add_f32_e32 v80, v96, v215
	v_add_f32_e32 v80, 0, v80
	v_sub_f32_e32 v10, v130, v194
	v_add_f32_e32 v81, v97, v216
	v_add_f32_e32 v80, v81, v80
	v_sub_f32_e32 v81, v98, v195
	v_exp_f32_e32 v98, v81
	v_sub_f32_e32 v81, v82, v195
	v_exp_f32_e32 v82, v81
	v_exp_f32_e32 v189, v10
	v_sub_f32_e32 v10, v114, v194
	v_exp_f32_e32 v199, v10
	v_add_f32_e32 v81, v98, v82
	v_add_f32_e32 v80, v81, v80
	v_sub_f32_e32 v81, v99, v195
	v_exp_f32_e32 v99, v81
	v_sub_f32_e32 v81, v83, v195
	v_exp_f32_e32 v83, v81
	v_sub_f32_e32 v10, v131, v194
	v_exp_f32_e32 v130, v10
	v_sub_f32_e32 v10, v115, v194
	v_add_f32_e32 v81, v99, v83
	v_add_f32_e32 v80, v81, v80
	v_sub_f32_e32 v81, v100, v195
	v_exp_f32_e32 v100, v81
	v_sub_f32_e32 v81, v84, v195
	v_exp_f32_e32 v217, v81
	v_exp_f32_e32 v184, v10
	v_sub_f32_e32 v10, v132, v194
	v_exp_f32_e32 v201, v10
	v_add_f32_e32 v81, v100, v217
	v_add_f32_e32 v80, v81, v80
	v_sub_f32_e32 v81, v101, v195
	v_exp_f32_e32 v84, v81
	v_sub_f32_e32 v81, v85, v195
	v_exp_f32_e32 v101, v81
	v_sub_f32_e32 v10, v116, v194
	v_exp_f32_e32 v204, v10
	v_sub_f32_e32 v10, v133, v194
	v_add_f32_e32 v81, v84, v101
	v_add_f32_e32 v80, v81, v80
	v_sub_f32_e32 v81, v102, v195
	v_exp_f32_e32 v85, v81
	v_sub_f32_e32 v81, v86, v195
	v_exp_f32_e32 v102, v81
	v_exp_f32_e32 v132, v10
	v_sub_f32_e32 v10, v117, v194
	v_exp_f32_e32 v186, v10
	v_add_f32_e32 v81, v85, v102
	v_add_f32_e32 v80, v81, v80
	v_sub_f32_e32 v81, v103, v195
	v_exp_f32_e32 v86, v81
	v_sub_f32_e32 v81, v87, v195
	v_exp_f32_e32 v87, v81
	v_sub_f32_e32 v10, v134, v194
	v_exp_f32_e32 v205, v10
	v_sub_f32_e32 v10, v118, v194
	v_add_f32_e32 v81, v86, v87
	v_add_f32_e32 v80, v81, v80
	v_sub_f32_e32 v81, v104, v195
	v_exp_f32_e32 v103, v81
	v_sub_f32_e32 v81, v88, v195
	v_exp_f32_e32 v104, v81
	v_exp_f32_e32 v206, v10
	v_sub_f32_e32 v10, v135, v194
	v_exp_f32_e32 v134, v10
	v_add_f32_e32 v81, v103, v104
	v_add_f32_e32 v80, v81, v80
	v_sub_f32_e32 v81, v105, v195
	v_exp_f32_e32 v88, v81
	v_sub_f32_e32 v81, v89, v195
	v_exp_f32_e32 v105, v81
	v_sub_f32_e32 v10, v119, v194
	v_exp_f32_e32 v188, v10
	v_sub_f32_e32 v10, v136, v194
	v_add_f32_e32 v81, v88, v105
	v_add_f32_e32 v80, v81, v80
	v_sub_f32_e32 v81, v106, v195
	v_exp_f32_e32 v89, v81
	v_sub_f32_e32 v81, v90, v195
	v_exp_f32_e32 v106, v81
	v_exp_f32_e32 v207, v10
	v_sub_f32_e32 v10, v120, v194
	v_exp_f32_e32 v208, v10
	v_add_f32_e32 v81, v89, v106
	v_add_f32_e32 v80, v81, v80
	v_sub_f32_e32 v81, v107, v195
	v_exp_f32_e32 v90, v81
	v_sub_f32_e32 v81, v91, v195
	v_exp_f32_e32 v107, v81
	v_sub_f32_e32 v10, v137, v194
	v_exp_f32_e32 v136, v10
	v_sub_f32_e32 v10, v121, v194
	v_add_f32_e32 v81, v90, v107
	v_add_f32_e32 v80, v81, v80
	v_sub_f32_e32 v81, v108, v195
	v_exp_f32_e32 v91, v81
	v_sub_f32_e32 v81, v92, v195
	v_exp_f32_e32 v108, v81
	v_sub_f32_e32 v0, v128, v194
	v_exp_f32_e32 v198, v10
	v_sub_f32_e32 v10, v138, v194
	v_add_f32_e32 v81, v91, v108
	v_add_f32_e32 v80, v81, v80
	v_sub_f32_e32 v81, v109, v195
	v_exp_f32_e32 v109, v81
	v_sub_f32_e32 v81, v93, v195
	v_exp_f32_e32 v219, v81
	v_exp_f32_e32 v15, v0
	v_sub_f32_e32 v0, v112, v194
	v_exp_f32_e32 v209, v10
	v_add_f32_e32 v81, v109, v219
	v_add_f32_e32 v80, v81, v80
	v_sub_f32_e32 v81, v110, v195
	v_exp_f32_e32 v110, v81
	v_sub_f32_e32 v81, v94, v195
	v_exp_f32_e32 v220, v81
	v_sub_f32_e32 v10, v122, v194
	v_exp_f32_e32 v187, v0
	v_sub_f32_e32 v0, v129, v194
	v_exp_f32_e32 v210, v10
	v_sub_f32_e32 v10, v139, v194
	v_add_f32_e32 v81, v110, v220
	v_exp_f32_e32 v128, v0
	v_exp_f32_e32 v138, v10
	v_sub_f32_e32 v10, v123, v194
	v_add_f32_e32 v80, v81, v80
	v_sub_f32_e32 v81, v111, v195
	v_exp_f32_e32 v200, v10
	v_sub_f32_e32 v10, v140, v194
	v_exp_f32_e32 v111, v81
	v_sub_f32_e32 v81, v95, v195
	v_cvt_pk_bf16_f32 v92, v96, v97
	v_cvt_pk_bf16_f32 v93, v98, v99
	v_cvt_pk_bf16_f32 v94, v100, v84
	v_cvt_pk_bf16_f32 v95, v85, v86
	v_cvt_pk_bf16_f32 v88, v103, v88
	v_cvt_pk_bf16_f32 v86, v217, v101
	v_cvt_pk_bf16_f32 v87, v102, v87
	ds_read_b128 v[96:99], v202 offset:18432
	ds_read_b128 v[100:103], v202 offset:18464
	v_sub_f32_e32 v0, v113, v194
	v_exp_f32_e32 v211, v10
	v_sub_f32_e32 v10, v124, v194
	v_exp_f32_e32 v221, v81
	v_exp_f32_e32 v0, v0
	v_exp_f32_e32 v212, v10
	v_sub_f32_e32 v10, v141, v194
	v_exp_f32_e32 v124, v10
	v_sub_f32_e32 v10, v125, v194
	v_cvt_pk_bf16_f32 v120, v15, v128
	v_cvt_pk_bf16_f32 v121, v189, v130
	v_cvt_pk_bf16_f32 v122, v201, v132
	v_cvt_pk_bf16_f32 v123, v205, v134
	v_exp_f32_e32 v140, v10
	v_sub_f32_e32 v10, v142, v194
	s_waitcnt lgkmcnt(1)
	v_mfma_f32_32x32x16_bf16 v[64:79], v[96:99], v[120:123], v[64:79]
	v_exp_f32_e32 v213, v10
	v_sub_f32_e32 v10, v126, v194
	v_add_f32_e32 v81, v111, v221
	v_add_f32_e32 v129, v15, v187
	v_exp_f32_e32 v214, v10
	v_sub_f32_e32 v10, v143, v194
	v_add_f32_e32 v191, v81, v80
	v_mfma_f32_32x32x16_bf16 v[32:47], v[96:99], v[92:95], v[32:47]
	v_add_f32_e64 v80, v128, v0
	v_add_f32_e64 v81, v129, v1
	v_exp_f32_e32 v126, v10
	v_pk_add_f32 v[80:81], v[80:81], v[80:81] op_sel_hi:[0,1]
	v_fmac_f32_e32 v191, v185, v182
	v_add_f32_e32 v131, v189, v199
	v_mov_b32_e32 v185, v81
	v_pk_add_f32 v[80:81], v[130:131], v[184:185]
	v_cvt_pk_bf16_f32 v116, v207, v136
	v_pk_add_f32 v[80:81], v[80:81], v[80:81] op_sel_hi:[0,1]
	v_cvt_pk_bf16_f32 v117, v209, v138
	v_cvt_pk_bf16_f32 v118, v211, v124
	v_cvt_pk_bf16_f32 v119, v213, v126
	v_cvt_pk_bf16_f32 v112, v187, v0
	v_add_f32_e32 v133, v201, v204
	v_mov_b32_e32 v187, v81
	v_cvt_pk_bf16_f32 v89, v89, v90
	v_cvt_pk_bf16_f32 v90, v91, v109
	v_cvt_pk_bf16_f32 v91, v110, v111
	ds_read_b128 v[96:99], v202 offset:18496
	v_pk_add_f32 v[80:81], v[132:133], v[186:187]
	s_waitcnt lgkmcnt(1)
	v_mfma_f32_32x32x16_bf16 v[64:79], v[100:103], v[116:119], v[64:79]
	v_pk_add_f32 v[80:81], v[80:81], v[80:81] op_sel_hi:[0,1]
	v_add_f32_e32 v135, v205, v206
	v_mov_b32_e32 v189, v81
	v_pk_add_f32 v[80:81], v[134:135], v[188:189]
	v_cvt_pk_bf16_f32 v113, v199, v184
	v_pk_add_f32 v[80:81], v[80:81], v[80:81] op_sel_hi:[0,1]
	v_add_f32_e32 v137, v207, v208
	v_mfma_f32_32x32x16_bf16 v[32:47], v[100:103], v[88:91], v[32:47]
	v_mov_b32_e32 v199, v81
	v_add_f32_e64 v80, v136, v198
	v_add_f32_e64 v81, v137, v199
	v_cvt_pk_bf16_f32 v114, v204, v186
	v_cvt_pk_bf16_f32 v115, v206, v188
	v_pk_add_f32 v[80:81], v[80:81], v[80:81] op_sel_hi:[0,1]
	v_cvt_pk_bf16_f32 v84, v215, v216
	v_cvt_pk_bf16_f32 v85, v82, v83
	v_add_f32_e32 v139, v209, v210
	v_mov_b32_e32 v201, v81
	s_waitcnt lgkmcnt(0)
	v_mfma_f32_32x32x16_bf16 v[64:79], v[96:99], v[112:115], v[64:79]
	v_add_f32_e64 v80, v138, v200
	v_add_f32_e64 v81, v139, v201
	v_sub_f32_e32 v10, v127, v194
	v_pk_add_f32 v[80:81], v[80:81], v[80:81] op_sel_hi:[0,1]
	v_exp_f32_e32 v142, v10
	v_add_f32_e32 v125, v211, v212
	v_mov_b32_e32 v141, v81
	v_pk_add_f32 v[80:81], v[124:125], v[140:141]
	v_mfma_f32_32x32x16_bf16 v[32:47], v[96:99], v[84:87], v[32:47]
	ds_read_b128 v[96:99], v202 offset:18528
	v_pk_add_f32 v[80:81], v[80:81], v[80:81] op_sel_hi:[0,1]
	v_add_f32_e32 v127, v213, v214
	v_mov_b32_e32 v143, v81
	v_pk_add_f32 v[80:81], v[126:127], v[142:143]
	v_cvt_pk_bf16_f32 v10, v208, v198
	v_cvt_pk_bf16_f32 v11, v210, v200
	v_cvt_pk_bf16_f32 v12, v212, v140
	v_cvt_pk_bf16_f32 v13, v214, v142
	v_add_f32_e32 v15, v80, v81
	v_cvt_pk_bf16_f32 v80, v104, v105
	v_cvt_pk_bf16_f32 v81, v106, v107
	v_cvt_pk_bf16_f32 v82, v108, v219
	v_cvt_pk_bf16_f32 v83, v220, v221
	s_waitcnt lgkmcnt(0)
	v_mfma_f32_32x32x16_bf16 v[64:79], v[96:99], v[10:13], v[64:79]
	s_xor_b32 s1, s1, 1
	s_mulk_i32 s1, 0x2400
	s_add_i32 s0, s0, 1
	v_add_u32_e32 v0, s1, v193
	s_mov_b64 s[34:35], 0x8000
	v_fmac_f32_e32 v15, v203, v14
	v_add_u32_e32 v0, 0x4800, v0
	v_mfma_f32_32x32x16_bf16 v[32:47], v[96:99], v[80:83], v[32:47]
	ds_read_b128 v[96:99], v202 offset:23040
	v_lshl_add_u64 v[178:179], v[178:179], 0, s[84:85]
	s_cmpk_eq_i32 s0, 0x47
	s_waitcnt lgkmcnt(0)
	v_mfma_f32_32x32x16_bf16 v[16:31], v[96:99], v[92:95], v[16:31]
	ds_read_b128 v[92:95], v202 offset:23072
	v_mfma_f32_32x32x16_bf16 v[48:63], v[96:99], v[120:123], v[48:63]
	s_waitcnt lgkmcnt(0)
	v_mfma_f32_32x32x16_bf16 v[16:31], v[92:95], v[88:91], v[16:31]
	ds_read_b128 v[88:91], v202 offset:23104
	v_mfma_f32_32x32x16_bf16 v[48:63], v[92:95], v[116:119], v[48:63]
	s_waitcnt lgkmcnt(0)
	v_mfma_f32_32x32x16_bf16 v[16:31], v[88:91], v[84:87], v[16:31]
	ds_read_b128 v[84:87], v202 offset:23136
	s_waitcnt vmcnt(1)
	ds_write2_b64 v0, v[2:3], v[4:5] offset1:2
	v_mfma_f32_32x32x16_bf16 v[48:63], v[88:91], v[112:115], v[48:63]
	s_waitcnt lgkmcnt(1)
	v_mfma_f32_32x32x16_bf16 v[48:63], v[84:87], v[10:13], v[48:63]
	s_waitcnt lgkmcnt(0)
	s_barrier
	v_mfma_f32_32x32x16_bf16 v[16:31], v[84:87], v[80:83], v[16:31]
	s_cbranch_scc1 .LBB0_112
	v_mov_b32_e32 v182, v195
	v_mov_b32_e32 v185, v191
	v_mov_b32_e32 v203, v15
	s_branch .LBB0_106
.LBB0_112:
	s_waitcnt vmcnt(0)
	s_cmpk_lt_u32 s101, 0x100
	s_cbranch_scc0 .Lgqa_stag_out
	s_barrier

.LBB0_179:
	s_or_b64 exec, exec, s[4:5]
	s_lshl_b32 s31, s1, 6
	v_lshlrev_b32_e32 v12, 3, v10
	v_add_u32_e32 v13, s31, v65
	v_mov_b64_e32 v[10:11], s[8:9]
	v_mad_i64_i32 v[10:11], s[4:5], v13, s68, v[10:11]
	s_ashr_i32 s1, s0, 31
	v_lshl_add_u64 v[10:11], s[0:1], 1, v[10:11]
	v_lshlrev_b32_e32 v12, 1, v12
	v_mov_b32_e32 v13, v1
	v_lshl_add_u64 v[10:11], v[10:11], 0, v[12:13]
	global_load_dwordx4 v[10:13], v[10:11], off
	s_movk_i32 s4, 0xd0
	v_mul_u32_u24_e32 v63, 0xd0, v64
	v_mad_u64_u32 v[202:203], s[4:5], v65, s4, v[60:61]
	v_add_u32_e32 v67, 0, v202
	v_add_u32_e32 v223, v62, v63
	s_waitcnt vmcnt(0)
	ds_write_b128 v67, v[54:57]
	s_and_saveexec_b64 s[4:5], vcc
	s_xor_b64 s[4:5], exec, s[4:5]
	v_add_u32_e32 v223, v62, v63
	s_andn2_saveexec_b64 s[4:5], s[4:5]
	v_add_u32_e32 v54, 0, v223
	ds_write_b128 v54, v[144:147] offset:128
	s_or_b64 exec, exec, s[4:5]
	v_and_b32_e32 v79, 0xffff0000, v50
	v_lshlrev_b32_e32 v78, 16, v50
	s_mov_b32 s36, 0x3e16c740
	v_pk_mul_f32 v[78:79], v[78:79], s[36:37] op_sel_hi:[1,0]
	v_add_u32_e32 v54, s35, v221
	v_cvt_pk_bf16_f32 v160, v78, v79
	v_and_b32_e32 v79, 0xffff0000, v51
	v_lshlrev_b32_e32 v78, 16, v51
	v_pk_mul_f32 v[50:51], v[78:79], s[36:37] op_sel_hi:[1,0]
	v_ashrrev_i32_e32 v54, 6, v54
	v_cvt_pk_bf16_f32 v161, v50, v51
	v_and_b32_e32 v51, 0xffff0000, v52
	v_lshlrev_b32_e32 v50, 16, v52
	v_pk_mul_f32 v[50:51], v[50:51], s[36:37] op_sel_hi:[1,0]
	v_cvt_f32_i32_e32 v67, v54
	v_cvt_pk_bf16_f32 v162, v50, v51
	v_and_b32_e32 v51, 0xffff0000, v53
	v_lshlrev_b32_e32 v50, 16, v53
	v_pk_mul_f32 v[50:51], v[50:51], s[36:37] op_sel_hi:[1,0]
	v_and_b32_e32 v203, 31, v221
	v_cvt_pk_bf16_f32 v163, v50, v51
	v_and_b32_e32 v51, 0xffff0000, v46
	v_lshlrev_b32_e32 v50, 16, v46
	v_pk_mul_f32 v[50:51], v[50:51], s[36:37] op_sel_hi:[1,0]
	v_exp_f32_e32 v80, 0xbfd49a78
	v_cvt_pk_bf16_f32 v156, v50, v51
	v_and_b32_e32 v51, 0xffff0000, v47
	v_lshlrev_b32_e32 v50, 16, v47
	v_pk_mul_f32 v[46:47], v[50:51], s[36:37] op_sel_hi:[1,0]
	v_cvt_f32_ubyte0_e32 v54, v203
	v_cvt_pk_bf16_f32 v157, v46, v47
	v_and_b32_e32 v47, 0xffff0000, v48
	v_lshlrev_b32_e32 v46, 16, v48
	v_pk_mul_f32 v[46:47], v[46:47], s[36:37] op_sel_hi:[1,0]
	v_cmp_eq_u32_e32 vcc, 0, v220
	v_cvt_pk_bf16_f32 v158, v46, v47
	v_and_b32_e32 v47, 0xffff0000, v49
	v_lshlrev_b32_e32 v46, 16, v49
	v_pk_mul_f32 v[46:47], v[46:47], s[36:37] op_sel_hi:[1,0]
	v_cndmask_b32_e32 v75, v54, v67, vcc
	v_cvt_pk_bf16_f32 v159, v46, v47
	v_and_b32_e32 v47, 0xffff0000, v42
	v_lshlrev_b32_e32 v46, 16, v42
	v_pk_mul_f32 v[46:47], v[46:47], s[36:37] op_sel_hi:[1,0]
	v_mul_f32_e32 v55, 0.15915494, v75
	v_cvt_pk_bf16_f32 v164, v46, v47
	v_and_b32_e32 v47, 0xffff0000, v43
	v_lshlrev_b32_e32 v46, 16, v43
	v_pk_mul_f32 v[42:43], v[46:47], s[36:37] op_sel_hi:[1,0]
	v_exp_f32_e32 v81, 0xc0549a78
	v_cvt_pk_bf16_f32 v165, v42, v43
	v_and_b32_e32 v43, 0xffff0000, v44
	v_lshlrev_b32_e32 v42, 16, v44
	v_pk_mul_f32 v[42:43], v[42:43], s[36:37] op_sel_hi:[1,0]
	v_cos_f32_e32 v54, v55
	v_cvt_pk_bf16_f32 v166, v42, v43
	v_and_b32_e32 v43, 0xffff0000, v45
	v_lshlrev_b32_e32 v42, 16, v45
	v_pk_mul_f32 v[42:43], v[42:43], s[36:37] op_sel_hi:[1,0]
	v_sin_f32_e32 v56, v55
	v_cvt_pk_bf16_f32 v167, v42, v43
	v_and_b32_e32 v43, 0xffff0000, v38
	v_lshlrev_b32_e32 v42, 16, v38
	v_pk_mul_f32 v[42:43], v[42:43], s[36:37] op_sel_hi:[1,0]
	v_mul_f32_e32 v55, v80, v75
	v_cvt_pk_bf16_f32 v152, v42, v43
	v_and_b32_e32 v43, 0xffff0000, v39
	v_lshlrev_b32_e32 v42, 16, v39
	v_mul_f32_e32 v57, 0.15915494, v55
	v_exp_f32_e32 v82, 0xc09f73da
	v_pk_mul_f32 v[38:39], v[42:43], s[36:37] op_sel_hi:[1,0]
	v_and_b32_e32 v47, 0xffff0000, v26
	v_lshlrev_b32_e32 v46, 16, v26
	v_cos_f32_e32 v55, v57
	v_sin_f32_e32 v57, v57
	v_cvt_pk_bf16_f32 v153, v38, v39
	v_and_b32_e32 v39, 0xffff0000, v40
	v_lshlrev_b32_e32 v38, 16, v40
	v_pk_mul_f32 v[46:47], v[46:47], s[36:37] op_sel_hi:[1,0]
	v_mul_f32_e32 v62, v81, v75
	v_exp_f32_e32 v83, 0xc0d49a78
	v_pk_mul_f32 v[38:39], v[38:39], s[36:37] op_sel_hi:[1,0]
	v_cvt_pk_bf16_f32 v188, v46, v47
	v_and_b32_e32 v47, 0xffff0000, v27
	v_lshlrev_b32_e32 v46, 16, v27
	v_mul_f32_e32 v63, 0.15915494, v62
	v_cvt_pk_bf16_f32 v154, v38, v39
	v_and_b32_e32 v39, 0xffff0000, v41
	v_lshlrev_b32_e32 v38, 16, v41
	v_pk_mul_f32 v[26:27], v[46:47], s[36:37] op_sel_hi:[1,0]
	v_cos_f32_e32 v62, v63
	v_sin_f32_e32 v68, v63
	v_mul_f32_e32 v63, v82, v75
	v_exp_f32_e32 v84, 0xc104e08b
	v_pk_mul_f32 v[38:39], v[38:39], s[36:37] op_sel_hi:[1,0]
	v_and_b32_e32 v41, 0xffff0000, v30
	v_lshlrev_b32_e32 v40, 16, v30
	v_cvt_pk_bf16_f32 v189, v26, v27
	v_and_b32_e32 v27, 0xffff0000, v28
	v_lshlrev_b32_e32 v26, 16, v28
	v_mul_f32_e32 v69, 0.15915494, v63
	v_cvt_pk_bf16_f32 v155, v38, v39
	v_and_b32_e32 v39, 0xffff0000, v34
	v_lshlrev_b32_e32 v38, 16, v34
	v_pk_mul_f32 v[42:43], v[54:55], v[40:41]
	v_pk_mul_f32 v[40:41], v[56:57], v[40:41]
	v_pk_mul_f32 v[26:27], v[26:27], s[36:37] op_sel_hi:[1,0]
	v_cos_f32_e32 v63, v69
	v_sin_f32_e32 v69, v69
	v_mul_f32_e32 v70, v83, v75
	v_pk_fma_f32 v[42:43], v[56:57], v[38:39], v[42:43]
	v_pk_fma_f32 v[38:39], v[54:55], v[38:39], v[40:41] neg_lo:[0,0,1] neg_hi:[0,0,1]
	v_cvt_pk_bf16_f32 v190, v26, v27
	v_and_b32_e32 v27, 0xffff0000, v29
	v_lshlrev_b32_e32 v26, 16, v29
	v_mul_f32_e32 v71, 0.15915494, v70
	v_pk_mul_f32 v[38:39], v[38:39], s[36:37] op_sel_hi:[1,0]
	v_pk_mul_f32 v[26:27], v[26:27], s[36:37] op_sel_hi:[1,0]
	v_cos_f32_e32 v70, v71
	v_sin_f32_e32 v72, v71
	v_mul_f32_e32 v71, v84, v75
	v_exp_f32_e32 v85, 0xc11f73da
	v_cvt_pk_bf16_f32 v168, v38, v39
	v_pk_mul_f32 v[38:39], v[42:43], s[36:37] op_sel_hi:[1,0]
	v_cvt_pk_bf16_f32 v191, v26, v27
	v_and_b32_e32 v27, 0xffff0000, v22
	v_lshlrev_b32_e32 v26, 16, v22
	v_mul_f32_e32 v73, 0.15915494, v71
	v_cvt_pk_bf16_f32 v148, v38, v39
	v_and_b32_e32 v39, 0xffff0000, v35
	v_lshlrev_b32_e32 v38, 16, v35
	v_and_b32_e32 v35, 0xffff0000, v31
	v_lshlrev_b32_e32 v34, 16, v31
	v_pk_mul_f32 v[26:27], v[26:27], s[36:37] op_sel_hi:[1,0]
	v_cos_f32_e32 v71, v73
	v_sin_f32_e32 v73, v73
	v_pk_mul_f32 v[30:31], v[62:63], v[34:35]
	v_pk_mul_f32 v[34:35], v[68:69], v[34:35]
	v_cvt_pk_bf16_f32 v184, v26, v27
	v_and_b32_e32 v27, 0xffff0000, v23
	v_lshlrev_b32_e32 v26, 16, v23
	v_pk_fma_f32 v[34:35], v[62:63], v[38:39], v[34:35] neg_lo:[0,0,1] neg_hi:[0,0,1]
	v_pk_mul_f32 v[22:23], v[26:27], s[36:37] op_sel_hi:[1,0]
	v_mul_f32_e32 v74, v85, v75
	v_mul_f32_e32 v75, v218, v75
	v_pk_fma_f32 v[30:31], v[68:69], v[38:39], v[30:31]
	v_pk_mul_f32 v[34:35], v[34:35], s[36:37] op_sel_hi:[1,0]
	v_cvt_pk_bf16_f32 v185, v22, v23
	v_and_b32_e32 v23, 0xffff0000, v24
	v_lshlrev_b32_e32 v22, 16, v24
	v_mul_f32_e32 v76, 0.15915494, v74
	v_mul_f32_e32 v77, 0.15915494, v75
	v_cvt_pk_bf16_f32 v169, v34, v35
	v_pk_mul_f32 v[30:31], v[30:31], s[36:37] op_sel_hi:[1,0]
	v_and_b32_e32 v35, 0xffff0000, v32
	v_lshlrev_b32_e32 v34, 16, v32
	v_pk_mul_f32 v[22:23], v[22:23], s[36:37] op_sel_hi:[1,0]
	v_cos_f32_e32 v74, v76
	v_sin_f32_e32 v76, v76
	v_cos_f32_e32 v75, v77
	v_sin_f32_e32 v77, v77
	v_cvt_pk_bf16_f32 v149, v30, v31
	v_and_b32_e32 v31, 0xffff0000, v36
	v_lshlrev_b32_e32 v30, 16, v36
	v_pk_mul_f32 v[38:39], v[70:71], v[34:35]
	v_pk_mul_f32 v[34:35], v[72:73], v[34:35]
	v_cvt_pk_bf16_f32 v186, v22, v23
	v_and_b32_e32 v23, 0xffff0000, v25
	v_lshlrev_b32_e32 v22, 16, v25
	v_pk_fma_f32 v[38:39], v[72:73], v[30:31], v[38:39]
	v_pk_fma_f32 v[30:31], v[70:71], v[30:31], v[34:35] neg_lo:[0,0,1] neg_hi:[0,0,1]
	v_pk_mul_f32 v[22:23], v[22:23], s[36:37] op_sel_hi:[1,0]
	v_pk_mul_f32 v[30:31], v[30:31], s[36:37] op_sel_hi:[1,0]
	v_cvt_pk_bf16_f32 v187, v22, v23
	v_and_b32_e32 v23, 0xffff0000, v18
	v_lshlrev_b32_e32 v22, 16, v18
	v_cvt_pk_bf16_f32 v170, v30, v31
	v_pk_mul_f32 v[30:31], v[38:39], s[36:37] op_sel_hi:[1,0]
	v_and_b32_e32 v35, 0xffff0000, v33
	v_lshlrev_b32_e32 v34, 16, v33
	v_pk_mul_f32 v[22:23], v[22:23], s[36:37] op_sel_hi:[1,0]
	v_cvt_pk_bf16_f32 v150, v30, v31
	v_and_b32_e32 v31, 0xffff0000, v37
	v_lshlrev_b32_e32 v30, 16, v37
	v_pk_mul_f32 v[32:33], v[74:75], v[34:35]
	v_pk_mul_f32 v[34:35], v[76:77], v[34:35]
	v_cvt_pk_bf16_f32 v192, v22, v23
	v_and_b32_e32 v23, 0xffff0000, v19
	v_lshlrev_b32_e32 v22, 16, v19
	v_pk_fma_f32 v[32:33], v[76:77], v[30:31], v[32:33]
	v_pk_fma_f32 v[30:31], v[74:75], v[30:31], v[34:35] neg_lo:[0,0,1] neg_hi:[0,0,1]
	v_pk_mul_f32 v[18:19], v[22:23], s[36:37] op_sel_hi:[1,0]
	v_pk_mul_f32 v[30:31], v[30:31], s[36:37] op_sel_hi:[1,0]
	v_cvt_pk_bf16_f32 v193, v18, v19
	v_and_b32_e32 v19, 0xffff0000, v20
	v_lshlrev_b32_e32 v18, 16, v20
	v_cvt_pk_bf16_f32 v171, v30, v31
	v_pk_mul_f32 v[30:31], v[32:33], s[36:37] op_sel_hi:[1,0]
	v_pk_mul_f32 v[18:19], v[18:19], s[36:37] op_sel_hi:[1,0]
	v_cvt_pk_bf16_f32 v151, v30, v31
	v_and_b32_e32 v30, 63, v66
	v_cvt_pk_bf16_f32 v194, v18, v19
	v_and_b32_e32 v19, 0xffff0000, v21
	v_lshlrev_b32_e32 v18, 16, v21
	v_cvt_f32_ubyte0_e32 v30, v30
	v_pk_mul_f32 v[18:19], v[18:19], s[36:37] op_sel_hi:[1,0]
	v_cndmask_b32_e32 v43, v30, v67, vcc
	v_cvt_pk_bf16_f32 v195, v18, v19
	v_and_b32_e32 v19, 0xffff0000, v14
	v_lshlrev_b32_e32 v18, 16, v14
	v_mul_f32_e32 v31, 0.15915494, v43
	v_pk_mul_f32 v[18:19], v[18:19], s[36:37] op_sel_hi:[1,0]
	v_cos_f32_e32 v30, v31
	v_sin_f32_e32 v32, v31
	v_mul_f32_e32 v31, v80, v43
	v_cvt_pk_bf16_f32 v180, v18, v19
	v_and_b32_e32 v19, 0xffff0000, v15
	v_lshlrev_b32_e32 v18, 16, v15
	v_mul_f32_e32 v33, 0.15915494, v31
	v_pk_mul_f32 v[14:15], v[18:19], s[36:37] op_sel_hi:[1,0]
	v_cos_f32_e32 v31, v33
	v_sin_f32_e32 v33, v33
	v_cvt_pk_bf16_f32 v181, v14, v15
	v_and_b32_e32 v15, 0xffff0000, v16
	v_lshlrev_b32_e32 v14, 16, v16
	v_mul_f32_e32 v34, v81, v43
	v_pk_mul_f32 v[14:15], v[14:15], s[36:37] op_sel_hi:[1,0]
	v_mul_f32_e32 v35, 0.15915494, v34
	v_cvt_pk_bf16_f32 v182, v14, v15
	v_and_b32_e32 v15, 0xffff0000, v17
	v_lshlrev_b32_e32 v14, 16, v17
	v_cos_f32_e32 v34, v35
	v_sin_f32_e32 v36, v35
	v_mul_f32_e32 v35, v82, v43
	v_pk_mul_f32 v[14:15], v[14:15], s[36:37] op_sel_hi:[1,0]
	v_and_b32_e32 v17, 0xffff0000, v2
	v_lshlrev_b32_e32 v16, 16, v2
	v_mul_f32_e32 v37, 0.15915494, v35
	v_cvt_pk_bf16_f32 v183, v14, v15
	v_and_b32_e32 v15, 0xffff0000, v6
	v_lshlrev_b32_e32 v14, 16, v6
	v_pk_mul_f32 v[18:19], v[30:31], v[16:17]
	v_pk_mul_f32 v[16:17], v[32:33], v[16:17]
	v_cos_f32_e32 v35, v37
	v_sin_f32_e32 v37, v37
	v_mul_f32_e32 v38, v83, v43
	v_pk_fma_f32 v[18:19], v[32:33], v[14:15], v[18:19]
	v_pk_fma_f32 v[14:15], v[30:31], v[14:15], v[16:17] neg_lo:[0,0,1] neg_hi:[0,0,1]
	v_mul_f32_e32 v39, 0.15915494, v38
	v_pk_mul_f32 v[14:15], v[14:15], s[36:37] op_sel_hi:[1,0]
	v_cos_f32_e32 v38, v39
	v_sin_f32_e32 v40, v39
	v_mul_f32_e32 v39, v84, v43
	v_cvt_pk_bf16_f32 v176, v14, v15
	v_pk_mul_f32 v[14:15], v[18:19], s[36:37] op_sel_hi:[1,0]
	v_mul_f32_e32 v41, 0.15915494, v39
	v_cvt_pk_bf16_f32 v172, v14, v15
	v_and_b32_e32 v15, 0xffff0000, v7
	v_lshlrev_b32_e32 v14, 16, v7
	v_and_b32_e32 v7, 0xffff0000, v3
	v_lshlrev_b32_e32 v6, 16, v3
	v_cos_f32_e32 v39, v41
	v_sin_f32_e32 v41, v41
	v_pk_mul_f32 v[2:3], v[34:35], v[6:7]
	v_pk_mul_f32 v[6:7], v[36:37], v[6:7]
	v_mul_f32_e32 v42, v85, v43
	v_pk_fma_f32 v[6:7], v[34:35], v[14:15], v[6:7] neg_lo:[0,0,1] neg_hi:[0,0,1]
	v_mul_f32_e32 v43, v218, v43
	v_pk_fma_f32 v[2:3], v[36:37], v[14:15], v[2:3]
	v_pk_mul_f32 v[6:7], v[6:7], s[36:37] op_sel_hi:[1,0]
	v_mul_f32_e32 v44, 0.15915494, v42
	v_mul_f32_e32 v45, 0.15915494, v43
	v_cvt_pk_bf16_f32 v177, v6, v7
	v_pk_mul_f32 v[2:3], v[2:3], s[36:37] op_sel_hi:[1,0]
	v_and_b32_e32 v7, 0xffff0000, v4
	v_lshlrev_b32_e32 v6, 16, v4
	v_cos_f32_e32 v42, v44
	v_sin_f32_e32 v44, v44
	v_cos_f32_e32 v43, v45
	v_sin_f32_e32 v45, v45
	v_cvt_pk_bf16_f32 v173, v2, v3
	v_and_b32_e32 v3, 0xffff0000, v8
	v_lshlrev_b32_e32 v2, 16, v8
	v_pk_mul_f32 v[14:15], v[38:39], v[6:7]
	v_pk_mul_f32 v[6:7], v[40:41], v[6:7]
	v_pk_fma_f32 v[14:15], v[40:41], v[2:3], v[14:15]
	v_pk_fma_f32 v[2:3], v[38:39], v[2:3], v[6:7] neg_lo:[0,0,1] neg_hi:[0,0,1]
	v_and_b32_e32 v7, 0xffff0000, v5
	v_pk_mul_f32 v[2:3], v[2:3], s[36:37] op_sel_hi:[1,0]
	v_lshlrev_b32_e32 v6, 16, v5
	v_cvt_pk_bf16_f32 v178, v2, v3
	v_pk_mul_f32 v[2:3], v[14:15], s[36:37] op_sel_hi:[1,0]
	v_pk_mul_f32 v[4:5], v[42:43], v[6:7]
	v_cvt_pk_bf16_f32 v174, v2, v3
	v_and_b32_e32 v3, 0xffff0000, v9
	v_lshlrev_b32_e32 v2, 16, v9
	v_pk_mul_f32 v[6:7], v[44:45], v[6:7]
	v_pk_fma_f32 v[4:5], v[44:45], v[2:3], v[4:5]
	v_pk_fma_f32 v[2:3], v[42:43], v[2:3], v[6:7] neg_lo:[0,0,1] neg_hi:[0,0,1]
	s_lshr_b32 s4, s28, 3
	v_pk_mul_f32 v[2:3], v[2:3], s[36:37] op_sel_hi:[1,0]
	s_and_b32 s5, s4, 15
	v_cvt_pk_bf16_f32 v179, v2, v3
	v_pk_mul_f32 v[2:3], v[4:5], s[36:37] op_sel_hi:[1,0]
	v_mul_lo_u32 v4, v65, s42
	v_cvt_pk_bf16_f32 v175, v2, v3
	v_and_b32_e32 v2, 0x60, v60
	v_lshlrev_b32_e32 v3, 3, v221
	v_and_b32_e32 v3, 8, v3
	v_add_u32_e32 v2, 0, v2
	v_add3_u32 v226, v2, v3, v4
	v_add_u32_e32 v2, 0x6800, v226
	s_waitcnt vmcnt(0)
	ds_write2_b64 v2, v[10:11], v[12:13] offset1:2
	v_mul_u32_u24_e32 v2, 0xd0, v203
	v_add3_u32 v225, 0, v2, v0
	v_lshlrev_b32_e32 v0, 6, v203
	v_sub_u32_e32 v222, v225, v0
	v_lshl_add_u32 v0, s5, 6, v65
	s_lshl_b32 s80, s5, 7
	v_mad_i64_i32 v[2:3], s[36:37], v0, s68, 0
	v_lshlrev_b32_e32 v0, 4, v221
	s_lshl_b64 s[0:1], s[0:1], 1
	v_and_b32_e32 v0, 0x70, v0
	s_add_u32 s0, s20, s0
	v_or_b32_e32 v2, v2, v0
	s_addc_u32 s1, s21, s1
	v_lshl_add_u64 v[204:205], s[0:1], 0, v[2:3]
	v_lshl_add_u64 v[2:3], v[58:59], 0, s[80:81]
	s_mul_i32 s0, s34, 0x1200
	v_lshl_add_u64 v[2:3], v[2:3], 0, v[0:1]
	s_addk_i32 s0, 0x2000
	v_lshl_add_u64 v[206:207], s[10:11], 0, v[2:3]
	v_or_b32_e32 v2, s0, v64
	v_ashrrev_i32_e32 v3, 31, v2
	v_lshlrev_b64 v[2:3], 6, v[2:3]
	v_lshl_or_b32 v2, v61, 4, v2
	v_mov_b32_e32 v14, v1
	v_mov_b32_e32 v15, v1
	v_lshl_add_u64 v[208:209], s[16:17], 0, v[2:3]
	v_mov_b32_e32 v0, v1
	v_mov_b32_e32 v2, v1
	v_mov_b32_e32 v3, v1
	v_mov_b32_e32 v4, v1
	v_mov_b32_e32 v5, v1
	v_mov_b32_e32 v6, v1
	v_mov_b32_e32 v7, v1
	v_mov_b32_e32 v8, v1
	v_mov_b32_e32 v9, v1
	v_mov_b32_e32 v10, v1
	v_mov_b32_e32 v11, v1
	v_mov_b32_e32 v12, v1
	v_mov_b32_e32 v13, v1
	v_mov_b64_e32 v[30:31], v[14:15]
	v_mov_b64_e32 v[46:47], v[14:15]
	v_mov_b64_e32 v[62:63], v[14:15]
	v_mov_b64_e32 v[78:79], v[14:15]
	s_mov_b32 s4, 0
	v_mov_b32_e32 v227, 0
	v_mov_b32_e32 v228, 0xf149f2ca
	v_mov_b64_e32 v[28:29], v[12:13]
	v_mov_b64_e32 v[26:27], v[10:11]
	v_mov_b64_e32 v[24:25], v[8:9]
	v_mov_b64_e32 v[22:23], v[6:7]
	v_mov_b64_e32 v[20:21], v[4:5]
	v_mov_b64_e32 v[18:19], v[2:3]
	v_mov_b64_e32 v[16:17], v[0:1]
	v_mov_b64_e32 v[44:45], v[12:13]
	v_mov_b64_e32 v[42:43], v[10:11]
	v_mov_b64_e32 v[40:41], v[8:9]
	v_mov_b64_e32 v[38:39], v[6:7]
	v_mov_b64_e32 v[36:37], v[4:5]
	v_mov_b64_e32 v[34:35], v[2:3]
	v_mov_b64_e32 v[32:33], v[0:1]
	v_mov_b64_e32 v[60:61], v[12:13]
	v_mov_b64_e32 v[58:59], v[10:11]
	v_mov_b64_e32 v[56:57], v[8:9]
	v_mov_b64_e32 v[54:55], v[6:7]
	v_mov_b64_e32 v[52:53], v[4:5]
	v_mov_b64_e32 v[50:51], v[2:3]
	v_mov_b64_e32 v[48:49], v[0:1]
	v_mov_b64_e32 v[76:77], v[12:13]
	v_mov_b64_e32 v[74:75], v[10:11]
	v_mov_b64_e32 v[72:73], v[8:9]
	v_mov_b64_e32 v[70:71], v[6:7]
	v_mov_b64_e32 v[68:69], v[4:5]
	v_mov_b64_e32 v[66:67], v[2:3]
	v_mov_b64_e32 v[64:65], v[0:1]
	v_mov_b32_e32 v0, 0xf149f2ca
	v_mov_b32_e32 v11, 0
	s_waitcnt lgkmcnt(0)
	s_barrier
	global_load_dwordx4 v[6:9], v[206:207], off
	s_cmp_eq_u64 s[6:7], 0
	s_cbranch_scc0 .Lmla_stag_in
	s_barrier
.Lmla_stag_in:
	s_and_saveexec_b64 s[0:1], s[6:7]
	s_cbranch_execz .LBB0_186
	s_branch .LBB0_185

.LBB0_190:
	s_xor_b32 vcc_lo, s0, 1
	s_mul_i32 vcc_lo, vcc_lo, 0x3400
	v_add_u32_e32 v219, vcc_lo, v202
	v_add_u32_e32 v253, vcc_lo, v223
	s_waitcnt vmcnt(1)
	ds_write_b128 v219, v[6:9]
	s_and_saveexec_b64 s[100:101], s[6:7]
	ds_write_b128 v253, v[144:147] offset:128
	s_or_b64 exec, exec, s[100:101]
	s_waitcnt lgkmcnt(0)
	s_barrier
	s_mul_i32 s1, s0, 0x2400
	v_sub_f32_e32 v14, v128, v12
	v_sub_f32_e32 v128, v130, v12
	v_sub_f32_e32 v130, v132, v12
	v_sub_f32_e32 v132, v134, v12
	v_sub_f32_e32 v134, v136, v12
	v_sub_f32_e32 v136, v138, v12
	v_sub_f32_e32 v138, v140, v12
	v_sub_f32_e32 v140, v142, v12
	v_add_u32_e32 v142, s1, v222
	ds_read_b128 v[244:247], v142 offset:26624
	ds_read_b128 v[248:251], v142 offset:26656
	v_sub_f32_e32 v15, v112, v12
	v_sub_f32_e32 v112, v129, v12
	v_sub_f32_e32 v129, v131, v12
	v_sub_f32_e32 v131, v133, v12
	v_sub_f32_e32 v133, v135, v12
	v_sub_f32_e32 v135, v137, v12
	v_sub_f32_e32 v137, v139, v12
	v_sub_f32_e32 v139, v141, v12
	v_sub_f32_e32 v141, v143, v12
	v_sub_f32_e32 v96, v96, v13
	v_sub_f32_e32 v97, v97, v13
	v_sub_f32_e32 v98, v98, v13
	v_sub_f32_e32 v99, v99, v13
	v_sub_f32_e32 v100, v100, v13
	v_sub_f32_e32 v101, v101, v13
	v_sub_f32_e32 v102, v102, v13
	v_sub_f32_e32 v143, v86, v13
	v_sub_f32_e32 v86, v103, v13
	v_exp_f32_e32 v14, v14
	v_exp_f32_e32 v112, v112
	v_exp_f32_e32 v128, v128
	v_exp_f32_e32 v129, v129
	v_exp_f32_e32 v130, v130
	v_exp_f32_e32 v131, v131
	v_exp_f32_e32 v132, v132
	v_exp_f32_e32 v133, v133
	v_exp_f32_e32 v96, v96
	v_exp_f32_e32 v97, v97
	v_exp_f32_e32 v98, v98
	v_exp_f32_e32 v99, v99
	v_exp_f32_e32 v100, v100
	v_exp_f32_e32 v101, v101
	v_exp_f32_e32 v102, v102
	v_exp_f32_e32 v86, v86
	v_cvt_pk_bf16_f32 v228, v14, v112
	v_cvt_pk_bf16_f32 v229, v128, v129
	v_cvt_pk_bf16_f32 v230, v130, v131
	v_cvt_pk_bf16_f32 v231, v132, v133
	v_cvt_pk_bf16_f32 v210, v96, v97
	v_cvt_pk_bf16_f32 v211, v98, v99
	v_cvt_pk_bf16_f32 v212, v100, v101
	v_cvt_pk_bf16_f32 v213, v102, v86
	s_waitcnt lgkmcnt(1)
	v_mfma_f32_32x32x16_bf16 v[64:79], v[244:247], v[228:231], v[64:79]
	v_sub_f32_e32 v103, v104, v13
	v_sub_f32_e32 v104, v105, v13
	v_sub_f32_e32 v105, v106, v13
	v_sub_f32_e32 v106, v107, v13
	v_sub_f32_e32 v107, v108, v13
	v_sub_f32_e32 v108, v109, v13
	v_sub_f32_e32 v109, v110, v13
	v_mfma_f32_32x32x16_bf16 v[32:47], v[244:247], v[210:213], v[32:47]
	v_sub_f32_e32 v110, v111, v13
	v_exp_f32_e32 v134, v134
	v_exp_f32_e32 v135, v135
	v_exp_f32_e32 v136, v136
	v_exp_f32_e32 v137, v137
	v_exp_f32_e32 v138, v138
	v_exp_f32_e32 v139, v139
	v_exp_f32_e32 v140, v140
	v_exp_f32_e32 v141, v141
	v_exp_f32_e32 v103, v103
	v_exp_f32_e32 v104, v104
	v_exp_f32_e32 v105, v105
	v_exp_f32_e32 v106, v106
	v_exp_f32_e32 v107, v107
	v_exp_f32_e32 v108, v108
	v_exp_f32_e32 v109, v109
	v_exp_f32_e32 v110, v110
	v_cvt_pk_bf16_f32 v232, v134, v135
	v_cvt_pk_bf16_f32 v233, v136, v137
	v_cvt_pk_bf16_f32 v234, v138, v139
	v_cvt_pk_bf16_f32 v235, v140, v141
	v_cvt_pk_bf16_f32 v244, v103, v104
	v_cvt_pk_bf16_f32 v245, v105, v106
	v_cvt_pk_bf16_f32 v246, v107, v108
	v_cvt_pk_bf16_f32 v247, v109, v110
	ds_read_b128 v[198:201], v142 offset:26688
	s_waitcnt lgkmcnt(1)
	v_mfma_f32_32x32x16_bf16 v[64:79], v[248:251], v[232:235], v[64:79]
	v_sub_f32_e32 v113, v113, v12
	v_sub_f32_e32 v114, v114, v12
	v_sub_f32_e32 v115, v115, v12
	v_sub_f32_e32 v116, v116, v12
	v_sub_f32_e32 v117, v117, v12
	v_sub_f32_e32 v118, v118, v12
	v_sub_f32_e32 v119, v119, v12
	v_mfma_f32_32x32x16_bf16 v[32:47], v[248:251], v[244:247], v[32:47]
	v_sub_f32_e32 v80, v80, v13
	v_sub_f32_e32 v81, v81, v13
	v_sub_f32_e32 v82, v82, v13
	v_sub_f32_e32 v83, v83, v13
	v_sub_f32_e32 v84, v84, v13
	v_sub_f32_e32 v85, v85, v13
	v_sub_f32_e32 v87, v87, v13
	v_exp_f32_e32 v15, v15
	v_exp_f32_e32 v113, v113
	v_exp_f32_e32 v114, v114
	v_exp_f32_e32 v115, v115
	v_exp_f32_e32 v116, v116
	v_exp_f32_e32 v117, v117
	v_exp_f32_e32 v118, v118
	v_exp_f32_e32 v119, v119
	v_exp_f32_e32 v80, v80
	v_exp_f32_e32 v81, v81
	v_exp_f32_e32 v82, v82
	v_exp_f32_e32 v83, v83
	v_exp_f32_e32 v84, v84
	v_exp_f32_e32 v85, v85
	v_exp_f32_e32 v111, v143
	v_exp_f32_e32 v87, v87
	v_cvt_pk_bf16_f32 v236, v15, v113
	v_cvt_pk_bf16_f32 v237, v114, v115
	v_cvt_pk_bf16_f32 v238, v116, v117
	v_cvt_pk_bf16_f32 v239, v118, v119
	ds_read_b128 v[248:251], v142 offset:26720
	v_cvt_pk_bf16_f32 v214, v80, v81
	v_cvt_pk_bf16_f32 v215, v82, v83
	v_cvt_pk_bf16_f32 v216, v84, v85
	v_cvt_pk_bf16_f32 v217, v111, v87
	s_waitcnt lgkmcnt(1)
	v_mfma_f32_32x32x16_bf16 v[64:79], v[198:201], v[236:239], v[64:79]
	v_sub_f32_e32 v120, v120, v12
	v_sub_f32_e32 v121, v121, v12
	v_sub_f32_e32 v122, v122, v12
	v_sub_f32_e32 v123, v123, v12
	v_sub_f32_e32 v124, v124, v12
	v_sub_f32_e32 v125, v125, v12
	v_sub_f32_e32 v126, v126, v12
	v_mfma_f32_32x32x16_bf16 v[32:47], v[198:201], v[214:217], v[32:47]
	v_sub_f32_e32 v127, v127, v12
	v_sub_f32_e32 v88, v88, v13
	v_sub_f32_e32 v89, v89, v13
	v_sub_f32_e32 v90, v90, v13
	v_sub_f32_e32 v91, v91, v13
	v_sub_f32_e32 v92, v92, v13
	v_sub_f32_e32 v93, v93, v13
	v_sub_f32_e32 v94, v94, v13
	v_sub_f32_e32 v95, v95, v13
	v_exp_f32_e32 v120, v120
	v_exp_f32_e32 v121, v121
	v_exp_f32_e32 v122, v122
	v_exp_f32_e32 v123, v123
	v_exp_f32_e32 v124, v124
	v_exp_f32_e32 v125, v125
	v_exp_f32_e32 v126, v126
	v_exp_f32_e32 v127, v127
	v_exp_f32_e32 v88, v88
	v_exp_f32_e32 v89, v89
	v_exp_f32_e32 v90, v90
	v_exp_f32_e32 v91, v91
	v_exp_f32_e32 v92, v92
	v_exp_f32_e32 v93, v93
	v_exp_f32_e32 v94, v94
	v_exp_f32_e32 v95, v95
	v_cvt_pk_bf16_f32 v240, v120, v121
	v_cvt_pk_bf16_f32 v241, v122, v123
	v_cvt_pk_bf16_f32 v242, v124, v125
	v_cvt_pk_bf16_f32 v243, v126, v127
	v_cvt_pk_bf16_f32 v198, v88, v89
	v_cvt_pk_bf16_f32 v199, v90, v91
	v_cvt_pk_bf16_f32 v200, v92, v93
	v_cvt_pk_bf16_f32 v201, v94, v95
	s_waitcnt lgkmcnt(0)
	v_mfma_f32_32x32x16_bf16 v[64:79], v[248:251], v[240:243], v[64:79]
	s_xor_b32 s5, s0, 1
	s_mul_i32 s0, s5, 0x3400
	s_add_i32 s34, s0, 0
	v_mfma_f32_32x32x16_bf16 v[32:47], v[248:251], v[198:201], v[32:47]
	ds_read_b128 v[248:251], v142 offset:31232
	s_waitcnt lgkmcnt(0)
	v_mfma_f32_32x32x16_bf16 v[16:31], v[248:251], v[210:213], v[16:31]
	ds_read_b128 v[210:213], v142 offset:31264
	v_mfma_f32_32x32x16_bf16 v[48:63], v[248:251], v[228:231], v[48:63]
	s_waitcnt lgkmcnt(0)
	v_mfma_f32_32x32x16_bf16 v[48:63], v[210:213], v[232:235], v[48:63]
	v_mfma_f32_32x32x16_bf16 v[16:31], v[210:213], v[244:247], v[16:31]
	ds_read_b128 v[210:213], v142 offset:31296
	s_waitcnt lgkmcnt(0)
	v_mfma_f32_32x32x16_bf16 v[48:63], v[210:213], v[236:239], v[48:63]
	v_mfma_f32_32x32x16_bf16 v[16:31], v[210:213], v[214:217], v[16:31]
	ds_read_b128 v[210:213], v142 offset:31328
	s_waitcnt lgkmcnt(0)
	v_mfma_f32_32x32x16_bf16 v[48:63], v[210:213], v[240:243], v[48:63]
	v_mfma_f32_32x32x16_bf16 v[16:31], v[210:213], v[198:201], v[16:31]
	v_add_f32_e32 v6, v96, v80
	v_add_f32_e32 v6, 0, v6
	v_add_f32_e32 v7, v97, v81
	v_add_f32_e32 v6, v7, v6
	v_add_f32_e32 v7, v98, v82
	v_add_f32_e32 v6, v7, v6
	v_add_f32_e32 v7, v99, v83
	v_add_f32_e32 v6, v7, v6
	v_add_f32_e32 v7, v100, v84
	v_add_f32_e32 v6, v7, v6
	v_add_f32_e32 v7, v101, v85
	v_add_f32_e32 v6, v7, v6
	v_add_f32_e32 v7, v102, v111
	v_add_f32_e32 v6, v7, v6
	v_add_f32_e32 v7, v86, v87
	v_add_f32_e32 v6, v7, v6
	v_add_f32_e32 v7, v103, v88
	v_add_f32_e32 v6, v7, v6
	v_add_f32_e32 v7, v104, v89
	v_add_f32_e32 v6, v7, v6
	v_add_f32_e32 v7, v105, v90
	v_add_f32_e32 v6, v7, v6
	v_add_f32_e32 v7, v106, v91
	v_add_f32_e32 v6, v7, v6
	v_add_f32_e32 v7, v107, v92
	v_add_f32_e32 v6, v7, v6
	v_add_f32_e32 v7, v108, v93
	v_add_f32_e32 v6, v7, v6
	v_add_f32_e32 v7, v109, v94
	v_add_f32_e32 v6, v7, v6
	v_add_f32_e32 v7, v110, v95
	v_add_f32_e32 v224, v7, v6
	v_add_f32_e32 v6, v14, v15
	v_add_f32_e32 v6, 0, v6
	v_add_f32_e32 v7, v112, v113
	v_add_f32_e32 v6, v7, v6
	v_add_f32_e32 v7, v128, v114
	v_add_f32_e32 v6, v7, v6
	v_add_f32_e32 v7, v129, v115
	v_add_f32_e32 v6, v7, v6
	v_add_f32_e32 v7, v130, v116
	v_add_f32_e32 v6, v7, v6
	v_add_f32_e32 v7, v131, v117
	v_add_f32_e32 v6, v7, v6
	v_add_f32_e32 v7, v132, v118
	v_add_f32_e32 v6, v7, v6
	v_add_f32_e32 v7, v133, v119
	v_add_f32_e32 v6, v7, v6
	v_add_f32_e32 v7, v134, v120
	v_add_f32_e32 v6, v7, v6
	v_add_f32_e32 v7, v135, v121
	v_add_f32_e32 v6, v7, v6
	v_add_f32_e32 v7, v136, v122
	v_add_f32_e32 v6, v7, v6
	v_add_f32_e32 v7, v137, v123
	v_add_f32_e32 v6, v7, v6
	v_add_f32_e32 v7, v138, v124
	v_add_f32_e32 v6, v7, v6
	v_add_f32_e32 v7, v139, v125
	v_add_f32_e32 v6, v7, v6
	v_add_f32_e32 v7, v140, v126
	v_add_f32_e32 v6, v7, v6
	v_add_f32_e32 v7, v141, v127
	s_mulk_i32 s5, 0x2400
	v_add_f32_e32 v15, v7, v6
	v_fmac_f32_e32 v15, v11, v0
	s_add_i32 s4, s4, 1
	v_add_u32_e32 v0, s5, v226
	v_fmac_f32_e32 v224, v227, v10
	v_add_u32_e32 v0, 0x6800, v0
	v_lshl_add_u64 v[204:205], v[204:205], 0, s[84:85]
	v_lshl_add_u64 v[206:207], v[206:207], 0, s[56:57]
	s_cmpk_eq_i32 s4, 0x47
	v_lshl_add_u64 v[208:209], v[208:209], 0, s[58:59]
	s_waitcnt vmcnt(0)
	ds_write2_b64 v0, v[2:3], v[4:5] offset1:2
	s_waitcnt lgkmcnt(0)
	s_barrier
	s_cbranch_scc0 .LBB0_184
	s_cmp_eq_u64 s[6:7], 0
	s_cbranch_scc1 .Lmla_stag_out
	s_barrier
.Lmla_stag_out:
	ds_read_b128 v[2:5], v225 offset:13312
	ds_read_b128 v[144:147], v225 offset:13472
	ds_read_b128 v[6:9], v225 offset:19968
	s_waitcnt lgkmcnt(2)
	v_mfma_f32_32x32x16_bf16 v[80:95], v[2:5], v[160:163], 0
	v_mfma_f32_32x32x16_bf16 v[112:127], v[2:5], v[188:191], 0
	ds_read_b128 v[2:5], v225 offset:13344
	s_waitcnt lgkmcnt(1)
	v_mfma_f32_32x32x16_bf16 v[96:111], v[6:9], v[160:163], 0
	v_mfma_f32_32x32x16_bf16 v[128:143], v[6:9], v[188:191], 0
	ds_read_b128 v[6:9], v225 offset:20000
	s_waitcnt lgkmcnt(1)
	v_mfma_f32_32x32x16_bf16 v[80:95], v[2:5], v[156:159], v[80:95]
	v_mfma_f32_32x32x16_bf16 v[112:127], v[2:5], v[184:187], v[112:127]
	ds_read_b128 v[2:5], v225 offset:13376
	s_waitcnt lgkmcnt(1)
	v_mfma_f32_32x32x16_bf16 v[96:111], v[6:9], v[156:159], v[96:111]
	v_mfma_f32_32x32x16_bf16 v[128:143], v[6:9], v[184:187], v[128:143]
	ds_read_b128 v[6:9], v225 offset:20032
	s_waitcnt lgkmcnt(1)
	v_mfma_f32_32x32x16_bf16 v[80:95], v[2:5], v[164:167], v[80:95]
	v_mfma_f32_32x32x16_bf16 v[112:127], v[2:5], v[192:195], v[112:127]
	ds_read_b128 v[2:5], v225 offset:13408
	s_waitcnt lgkmcnt(1)
	v_mfma_f32_32x32x16_bf16 v[96:111], v[6:9], v[164:167], v[96:111]
	v_mfma_f32_32x32x16_bf16 v[128:143], v[6:9], v[192:195], v[128:143]
	ds_read_b128 v[6:9], v225 offset:20064
	s_waitcnt lgkmcnt(1)
	v_mfma_f32_32x32x16_bf16 v[80:95], v[2:5], v[152:155], v[80:95]
	v_mfma_f32_32x32x16_bf16 v[112:127], v[2:5], v[180:183], v[112:127]
	ds_read_b128 v[2:5], v225 offset:13440
	s_waitcnt lgkmcnt(1)
	v_mfma_f32_32x32x16_bf16 v[96:111], v[6:9], v[152:155], v[96:111]
	ds_read_b128 v[152:155], v225 offset:20128
	v_mfma_f32_32x32x16_bf16 v[128:143], v[6:9], v[180:183], v[128:143]
	ds_read_b128 v[6:9], v225 offset:20096
	s_waitcnt lgkmcnt(2)
	v_mfma_f32_32x32x16_bf16 v[80:95], v[2:5], v[168:171], v[80:95]
	s_waitcnt lgkmcnt(0)
	v_mfma_f32_32x32x16_bf16 v[96:111], v[6:9], v[168:171], v[96:111]
	v_mfma_f32_32x32x16_bf16 v[80:95], v[144:147], v[148:151], v[80:95]
	v_mfma_f32_32x32x16_bf16 v[96:111], v[152:155], v[148:151], v[96:111]
	v_max3_f32 v0, v80, v96, v81
	s_nop 0
	v_max3_f32 v0, v0, v97, v82
	s_nop 0
	v_max3_f32 v0, v0, v98, v83
	s_nop 0
	v_max3_f32 v0, v0, v99, v84
	v_mfma_f32_32x32x16_bf16 v[112:127], v[2:5], v[176:179], v[112:127]
	v_max3_f32 v0, v0, v100, v85
	s_nop 7
	v_max_f32_e32 v2, v111, v111
	v_max3_f32 v0, v0, v101, v86
	s_nop 0
	v_max3_f32 v0, v0, v102, v87
	s_nop 0
	v_max3_f32 v0, v0, v103, v88
	v_mfma_f32_32x32x16_bf16 v[128:143], v[6:9], v[176:179], v[128:143]
	v_max3_f32 v0, v0, v104, v89
	s_nop 0
	v_max3_f32 v0, v0, v105, v90
	s_nop 0
	v_max3_f32 v0, v0, v106, v91
	s_nop 0
	v_max3_f32 v0, v0, v107, v92
	v_mfma_f32_32x32x16_bf16 v[112:127], v[144:147], v[172:175], v[112:127]
	v_max3_f32 v0, v0, v108, v93
	s_nop 0
	v_max3_f32 v0, v0, v109, v94
	s_nop 0
	v_max3_f32 v0, v0, v110, v95
	s_nop 0
	v_max_f32_e32 v0, v0, v0
	v_max_f32_e32 v0, v0, v2
	v_mov_b32_e32 v2, v0
	v_mfma_f32_32x32x16_bf16 v[128:143], v[152:155], v[172:175], v[128:143]
	v_nop
	v_nop
	v_permlane32_swap_b32 v0, v2
	s_nop 0
	v_max3_f32 v147, v12, v0, v2
	v_sub_f32_e32 v0, v12, v147
	v_exp_f32_e32 v14, v0
	s_nop 0
	v_cmp_neq_f32_e32 vcc, 1.0, v14
	s_cbranch_vccz .LBB0_195
	v_pk_mul_f32 v[78:79], v[78:79], v[14:15] op_sel_hi:[1,0]
	v_pk_mul_f32 v[76:77], v[76:77], v[14:15] op_sel_hi:[1,0]
	v_pk_mul_f32 v[74:75], v[74:75], v[14:15] op_sel_hi:[1,0]
	v_pk_mul_f32 v[72:73], v[72:73], v[14:15] op_sel_hi:[1,0]
	v_pk_mul_f32 v[70:71], v[70:71], v[14:15] op_sel_hi:[1,0]
	v_pk_mul_f32 v[68:69], v[68:69], v[14:15] op_sel_hi:[1,0]
	v_pk_mul_f32 v[66:67], v[66:67], v[14:15] op_sel_hi:[1,0]
	v_pk_mul_f32 v[64:65], v[64:65], v[14:15] op_sel_hi:[1,0]
	v_pk_mul_f32 v[62:63], v[62:63], v[14:15] op_sel_hi:[1,0]
	v_pk_mul_f32 v[60:61], v[60:61], v[14:15] op_sel_hi:[1,0]
	v_pk_mul_f32 v[58:59], v[58:59], v[14:15] op_sel_hi:[1,0]
	v_pk_mul_f32 v[56:57], v[56:57], v[14:15] op_sel_hi:[1,0]
	v_pk_mul_f32 v[54:55], v[54:55], v[14:15] op_sel_hi:[1,0]
	v_pk_mul_f32 v[52:53], v[52:53], v[14:15] op_sel_hi:[1,0]
	v_pk_mul_f32 v[50:51], v[50:51], v[14:15] op_sel_hi:[1,0]
	v_pk_mul_f32 v[48:49], v[48:49], v[14:15] op_sel_hi:[1,0]

.LBB0_707:
	s_and_b64 vcc, exec, s[0:1]
	s_cbranch_vccz .LBB0_801
	v_mov_b32_e32 v5, v197
	s_mov_b32 s0, s66
	s_mov_b32 s39, s66
	v_ashrrev_i32_e32 v4, 6, v5
	v_lshl_add_u32 v7, s0, 3, v4
	v_readlane_b32 s0, v254, 56
	s_mov_b32 s2, s0
	s_waitcnt lgkmcnt(0)
	s_lshl_b32 s40, s0, 3
	v_readlane_b32 s1, v254, 57
	s_add_u32 s0, s96, 0xf0
	s_addc_u32 s1, s97, 0
	s_mov_b32 s38, s2
	s_add_u32 s2, s26, 0x9840000
	s_addc_u32 s3, s27, 0
	s_add_u32 s4, s96, 0x120
	s_addc_u32 s5, s97, 0
	s_add_u32 s6, s26, 0x9a40000
	s_addc_u32 s7, s27, 0
	s_add_u32 s8, s96, 0xd0
	s_addc_u32 s9, s97, 0
	s_add_u32 s10, s26, 0x91c0000
	s_addc_u32 s11, s27, 0
	s_add_u32 s14, s96, 0xe8
	v_lshlrev_b32_e32 v2, 3, v5
	v_lshl_add_u32 v3, v4, 14, 0
	s_addc_u32 s15, s97, 0
	v_bfe_u32 v13, v5, 5, 1
	v_and_b32_e32 v0, 31, v5
	v_bfe_u32 v49, v5, 3, 3
	v_and_b32_e32 v2, 56, v2
	s_add_u32 s16, s26, 0x9240000
	v_lshl_add_u32 v8, v0, 2, v3
	v_mul_u32_u24_e32 v9, 0x84, v13
	v_mul_u32_u24_e32 v10, 0x84, v2
	v_lshlrev_b32_e32 v11, 2, v49
	v_and_b32_e32 v6, 63, v5
	s_addc_u32 s17, s27, 0
	v_or_b32_e32 v18, 2, v13
	v_or_b32_e32 v19, 4, v13
	v_or_b32_e32 v20, 6, v13
	v_or_b32_e32 v21, 8, v13
	v_or_b32_e32 v22, 10, v13
	v_or_b32_e32 v23, 12, v13
	v_or_b32_e32 v24, 14, v13
	v_or_b32_e32 v25, 16, v13
	v_or_b32_e32 v26, 18, v13
	v_or_b32_e32 v27, 20, v13
	v_or_b32_e32 v28, 22, v13
	v_or_b32_e32 v29, 24, v13
	v_or_b32_e32 v30, 26, v13
	v_or_b32_e32 v31, 28, v13
	v_or_b32_e32 v32, 30, v13
	v_or_b32_e32 v33, 32, v13
	v_or_b32_e32 v34, 34, v13
	v_or_b32_e32 v35, 36, v13
	v_or_b32_e32 v36, 38, v13
	v_or_b32_e32 v37, 40, v13
	v_or_b32_e32 v38, 42, v13
	v_or_b32_e32 v39, 44, v13
	v_or_b32_e32 v40, 46, v13
	v_or_b32_e32 v41, 48, v13
	v_or_b32_e32 v42, 50, v13
	v_or_b32_e32 v43, 52, v13
	v_or_b32_e32 v44, 54, v13
	v_or_b32_e32 v45, 56, v13
	v_or_b32_e32 v46, 58, v13
	v_or_b32_e32 v47, 60, v13
	v_or_b32_e32 v48, 62, v13
	v_add3_u32 v50, v3, v10, v11
	v_or_b32_e32 v51, 8, v49
	v_or_b32_e32 v52, 16, v49
	v_or_b32_e32 v53, 24, v49
	s_mov_b32 s41, 0
	s_mov_b32 s100, 0
	v_lshlrev_b32_e32 v0, 2, v0
	v_lshlrev_b32_e32 v2, 1, v2
	v_add_u32_e32 v54, v8, v9
	s_branch .LBB0_710

.LBB0_758:
	s_lshr_b32 s35, s43, 6
	s_mul_i32 s35, s35, s42
	v_add_u32_e32 v100, s100, v7
	v_and_b32_e32 v100, 0x7ff, v100
	s_sub_i32 s100, s100, s35
	s_and_b32 s100, s100, 0x7ff
	s_cmpk_lg_u32 s40, 0x800
	s_cselect_b32 s100, 0, s100
	v_cmp_gt_i32_e32 vcc, s35, v100
	s_and_saveexec_b64 s[24:25], vcc
	s_cbranch_execz .LBB0_709
	v_cvt_f32_u32_e32 v10, s42
	v_mov_b32_e32 v3, v1
	s_sub_i32 s36, 0, s42
	s_lshl_b32 s46, s42, 5
	v_rcp_iflag_f32_e32 v10, v10
	s_waitcnt lgkmcnt(0)
	v_lshl_add_u64 v[8:9], s[28:29], 0, v[0:1]
	v_lshlrev_b32_e32 v55, 5, v100
	s_lshl_b32 s37, s40, 5
	v_mul_f32_e32 v10, 0x4f7ffffe, v10
	v_cvt_u32_f32_e32 v12, v10
	v_lshl_add_u64 v[10:11], s[30:31], 0, v[2:3]
	s_mov_b64 s[28:29], 0
	s_sub_i32 s30, 0, s46
	v_mul_lo_u32 v3, s36, v12
	v_mul_hi_u32 v3, v12, v3
	v_add_u32_e32 v3, v12, v3
	v_mov_b32_e32 v12, v100
	s_branch .LBB0_761

	.amdhsa_kernel _Z10fwd_kernel4Args
		.amdhsa_group_segment_fixed_size 0
		.amdhsa_private_segment_fixed_size 0
		.amdhsa_kernarg_size 584
		.amdhsa_user_sgpr_count 2
		.amdhsa_user_sgpr_dispatch_ptr 0
		.amdhsa_user_sgpr_queue_ptr 0
		.amdhsa_user_sgpr_kernarg_segment_ptr 1
		.amdhsa_user_sgpr_dispatch_id 0
		.amdhsa_user_sgpr_kernarg_preload_length 0
		.amdhsa_user_sgpr_kernarg_preload_offset 0
		.amdhsa_user_sgpr_private_segment_size 0
		.amdhsa_uses_dynamic_stack 0
		.amdhsa_enable_private_segment 0
		.amdhsa_system_sgpr_workgroup_id_x 1
		.amdhsa_system_sgpr_workgroup_id_y 0
		.amdhsa_system_sgpr_workgroup_id_z 0
		.amdhsa_system_sgpr_workgroup_info 0
		.amdhsa_system_vgpr_workitem_id 2
		.amdhsa_next_free_vgpr 256
		.amdhsa_next_free_sgpr 102
		.amdhsa_accum_offset 256
		.amdhsa_reserve_vcc 1
		.amdhsa_float_round_mode_32 0
		.amdhsa_float_round_mode_16_64 0
		.amdhsa_float_denorm_mode_32 3
		.amdhsa_float_denorm_mode_16_64 3
		.amdhsa_dx10_clamp 1
		.amdhsa_ieee_mode 1
		.amdhsa_fp16_overflow 0
		.amdhsa_tg_split 0
		.amdhsa_exception_fp_ieee_invalid_op 0
		.amdhsa_exception_fp_denorm_src 0
		.amdhsa_exception_fp_ieee_div_zero 0
		.amdhsa_exception_fp_ieee_overflow 0
		.amdhsa_exception_fp_ieee_underflow 0
		.amdhsa_exception_fp_ieee_inexact 0
		.amdhsa_exception_int_div_zero 0
	.end_amdhsa_kernel

amdhsa.kernels:
  - .agpr_count:     0
    .args:
      - .offset:         0
        .size:           328
        .value_kind:     by_value
      - .offset:         328
        .size:           4
        .value_kind:     hidden_block_count_x
      - .offset:         332
        .size:           4
        .value_kind:     hidden_block_count_y
      - .offset:         336
        .size:           4
        .value_kind:     hidden_block_count_z
      - .offset:         340
        .size:           2
        .value_kind:     hidden_group_size_x
      - .offset:         342
        .size:           2
        .value_kind:     hidden_group_size_y
      - .offset:         344
        .size:           2
        .value_kind:     hidden_group_size_z
      - .offset:         346
        .size:           2
        .value_kind:     hidden_remainder_x
      - .offset:         348
        .size:           2
        .value_kind:     hidden_remainder_y
      - .offset:         350
        .size:           2
        .value_kind:     hidden_remainder_z
      - .offset:         368
        .size:           8
        .value_kind:     hidden_global_offset_x
      - .offset:         376
        .size:           8
        .value_kind:     hidden_global_offset_y
      - .offset:         384
        .size:           8
        .value_kind:     hidden_global_offset_z
      - .offset:         392
        .size:           2
        .value_kind:     hidden_grid_dims
      - .offset:         416
        .size:           8
        .value_kind:     hidden_multigrid_sync_arg
      - .offset:         448
        .size:           4
        .value_kind:     hidden_dynamic_lds_size
    .group_segment_fixed_size: 0
    .kernarg_segment_align: 8
    .kernarg_segment_size: 584
    .language:       OpenCL C
    .language_version:
      - 2
      - 0
    .max_flat_workgroup_size: 512
    .name:           _Z10fwd_kernel4Args
    .private_segment_fixed_size: 0
    .sgpr_count:     108
    .sgpr_spill_count: 114
    .symbol:         _Z10fwd_kernel4Args.kd
    .uniform_work_group_size: 1
    .uses_dynamic_stack: false
    .vgpr_count:     256
    .vgpr_spill_count: 0
    .wavefront_size: 64
